# aa1 + loop-edge rotation: GQA loop copy of region A laid out after the loop bottom (taken branch in front of barrier A), MLA loop-back barrier made the loop head with exit-path barrier copy
# baseline (speedup 1.0000x reference)
.LBB0_739:
	ds_read_b128 v[236:239], v200 offset:49152
	ds_read_b128 v[240:243], v208 offset:49152
	ds_read_b128 v[244:247], v207 offset:49152
	ds_read_b128 v[248:251], v206 offset:49152
	s_add_i32 s6, s14, -3
	s_waitcnt lgkmcnt(3)
	v_mfma_f32_32x32x16_bf16 v[80:95], v[236:239], v[124:127], 0
	ds_read_b128 v[236:239], v205 offset:49152
	v_exp_f32_e32 v158, v158
	v_exp_f32_e32 v159, v159
	v_add_f32_e32 v210, 0, v162
	s_waitcnt lgkmcnt(3)
	v_mfma_f32_32x32x16_bf16 v[80:95], v[240:243], v[120:123], v[80:95]
	ds_read_b128 v[240:243], v204 offset:49152
	v_exp_f32_e32 v156, v156
	v_exp_f32_e32 v157, v157
	v_add_f32_e32 v210, v216, v210
	s_waitcnt lgkmcnt(3)
	v_mfma_f32_32x32x16_bf16 v[80:95], v[244:247], v[116:119], v[80:95]
	ds_read_b128 v[244:247], v202 offset:49152
	v_exp_f32_e32 v150, v150
	v_exp_f32_e32 v151, v151
	v_add_f32_e32 v210, v163, v210
	s_waitcnt lgkmcnt(3)
	v_mfma_f32_32x32x16_bf16 v[80:95], v[248:251], v[112:115], v[80:95]
	ds_read_b128 v[248:251], v201 offset:49152
	v_exp_f32_e32 v148, v148
	v_exp_f32_e32 v149, v149
	v_add_f32_e32 v210, v177, v210
	s_waitcnt lgkmcnt(3)
	v_mfma_f32_32x32x16_bf16 v[80:95], v[236:239], v[108:111], v[80:95]
	ds_read_b128 v[236:239], v200 offset:57344
	v_exp_f32_e32 v146, v146
	v_exp_f32_e32 v147, v147
	v_add_f32_e32 v210, v164, v210
	s_waitcnt lgkmcnt(3)
	v_mfma_f32_32x32x16_bf16 v[80:95], v[240:243], v[104:107], v[80:95]
	ds_read_b128 v[240:243], v208 offset:57344
	v_exp_f32_e32 v160, v160
	v_exp_f32_e32 v161, v161
	v_add_f32_e32 v210, v176, v210
	s_waitcnt lgkmcnt(3)
	v_mfma_f32_32x32x16_bf16 v[80:95], v[244:247], v[100:103], v[80:95]
	ds_read_b128 v[244:247], v207 offset:57344
	v_exp_f32_e32 v154, v154
	v_exp_f32_e32 v155, v155
	v_add_f32_e32 v210, v165, v210
	s_waitcnt lgkmcnt(3)
	v_mfma_f32_32x32x16_bf16 v[80:95], v[248:251], v[96:99], v[80:95]
	ds_read_b128 v[248:251], v206 offset:57344
	v_exp_f32_e32 v152, v152
	v_exp_f32_e32 v153, v153
	v_add_f32_e32 v210, v175, v210
	s_waitcnt lgkmcnt(3)
	v_mfma_f32_32x32x16_bf16 v[64:79], v[236:239], v[124:127], 0
	ds_read_b128 v[236:239], v205 offset:57344
	v_add_f32_e32 v210, v166, v210
	v_add_f32_e32 v210, v173, v210
	v_add_f32_e32 v210, v167, v210
	v_add_f32_e32 v210, v172, v210
	v_add_f32_e32 v210, v168, v210
	s_waitcnt lgkmcnt(3)
	v_mfma_f32_32x32x16_bf16 v[64:79], v[240:243], v[120:123], v[64:79]
	ds_read_b128 v[240:243], v204 offset:57344
	v_add_f32_e32 v210, v171, v210
	v_add_f32_e32 v210, v169, v210
	v_add_f32_e32 v210, v170, v210
	v_add_f32_e32 v210, v158, v210
	v_add_f32_e32 v210, v159, v210
	s_waitcnt lgkmcnt(3)
	v_mfma_f32_32x32x16_bf16 v[64:79], v[244:247], v[116:119], v[64:79]
	ds_read_b128 v[244:247], v202 offset:57344
	v_add_f32_e32 v210, v156, v210
	v_add_f32_e32 v210, v157, v210
	v_add_f32_e32 v210, v150, v210
	v_add_f32_e32 v210, v151, v210
	v_add_f32_e32 v210, v148, v210
	s_waitcnt lgkmcnt(3)
	v_mfma_f32_32x32x16_bf16 v[64:79], v[248:251], v[112:115], v[64:79]
	ds_read_b128 v[248:251], v201 offset:57344
	v_add_f32_e32 v210, v149, v210
	v_add_f32_e32 v210, v146, v210
	v_add_f32_e32 v210, v147, v210
	v_add_f32_e32 v210, v160, v210
	v_add_f32_e32 v210, v161, v210
	s_waitcnt lgkmcnt(3)
	v_mfma_f32_32x32x16_bf16 v[64:79], v[236:239], v[108:111], v[64:79]
	v_add_f32_e32 v210, v154, v210
	v_add_f32_e32 v210, v155, v210
	v_add_f32_e32 v210, v152, v210
	v_add_f32_e32 v210, v153, v210
	v_mov_b32_e32 v211, v210
	s_waitcnt lgkmcnt(2)
	v_mfma_f32_32x32x16_bf16 v[64:79], v[240:243], v[104:107], v[64:79]
	v_cvt_pk_bf16_f32 v162, v162, v216
	v_cvt_pk_bf16_f32 v163, v163, v177
	v_cvt_pk_bf16_f32 v164, v164, v176
	v_permlane32_swap_b32_e32 v210, v211
	v_cvt_pk_bf16_f32 v165, v165, v175
	ds_read_b64_tr_b16 v[216:217], v193 offset:0
	ds_read_b64_tr_b16 v[218:219], v193 offset:0x800
	ds_read_b64_tr_b16 v[220:221], v193 offset:0x1000
	ds_read_b64_tr_b16 v[222:223], v193 offset:0x1800
	ds_read_b64_tr_b16 v[224:225], v193 offset:0x2000
	ds_read_b64_tr_b16 v[226:227], v193 offset:0x2800
	ds_read_b64_tr_b16 v[232:233], v193 offset:0x3000
	ds_read_b64_tr_b16 v[234:235], v193 offset:0x3800
	s_waitcnt lgkmcnt(9)
	v_mfma_f32_32x32x16_bf16 v[64:79], v[244:247], v[100:103], v[64:79]
	v_permlane32_swap_b32_e32 v162, v164
	v_cvt_pk_bf16_f32 v166, v166, v173
	v_cvt_pk_bf16_f32 v167, v167, v172
	v_cvt_pk_bf16_f32 v168, v168, v171
	v_cvt_pk_bf16_f32 v169, v169, v170
	s_waitcnt lgkmcnt(8)
	v_mfma_f32_32x32x16_bf16 v[64:79], v[248:251], v[96:99], v[64:79]
	v_cvt_pk_bf16_f32 v170, v158, v159
	v_cvt_pk_bf16_f32 v171, v156, v157
	v_cvt_pk_bf16_f32 v172, v150, v151
	v_cvt_pk_bf16_f32 v173, v148, v149
	v_cvt_pk_bf16_f32 v212, v146, v147
	s_waitcnt vmcnt(0)
	ds_write_b128 v198, v[136:139] offset:32768
	ds_write_b128 v199, v[140:143] offset:32768
	s_sub_i32 s7, s8, 64
	s_cmp_lt_u32 s6, 2
	s_cselect_b32 s6, s15, s7
	s_ashr_i32 s7, s6, 31
	s_mul_hi_u32 s100, s6, s40
	s_mul_i32 s101, s6, s41
	s_add_u32 s100, s100, s101
	s_mul_i32 s101, s7, s40
	s_add_u32 s100, s100, s101
	s_mul_i32 s6, s6, s40
	s_mov_b32 s7, s100
	s_lshl_b64 s[6:7], s[6:7], 1
	v_permlane32_swap_b32_e32 v163, v165
	s_waitcnt lgkmcnt(8)
	s_nop 0
	v_mfma_f32_32x32x16_bf16 v[48:63], v[162:165], v[216:219], v[48:63]
	ds_read_b64_tr_b16 v[216:217], v193 offset:0x200
	ds_read_b64_tr_b16 v[218:219], v193 offset:0xa00
	v_cvt_pk_bf16_f32 v213, v160, v161
	v_cvt_pk_bf16_f32 v214, v154, v155
	v_cvt_pk_bf16_f32 v215, v152, v153
	v_permlane32_swap_b32_e32 v166, v168
	v_permlane32_swap_b32_e32 v167, v169
	s_waitcnt lgkmcnt(8)
	s_nop 0
	v_mfma_f32_32x32x16_bf16 v[48:63], v[166:169], v[220:223], v[48:63]
	ds_read_b64_tr_b16 v[220:221], v193 offset:0x1200
	ds_read_b64_tr_b16 v[222:223], v193 offset:0x1a00
	v_permlane32_swap_b32_e32 v170, v172
	v_permlane32_swap_b32_e32 v171, v173
	v_permlane32_swap_b32_e32 v212, v214
	v_permlane32_swap_b32_e32 v213, v215
	v_lshl_add_u64 v[146:147], s[6:7], 0, v[178:179]
	s_waitcnt lgkmcnt(8)
	v_mfma_f32_32x32x16_bf16 v[48:63], v[170:173], v[224:227], v[48:63]
	ds_read_b64_tr_b16 v[224:225], v193 offset:0x2200
	ds_read_b64_tr_b16 v[226:227], v193 offset:0x2a00
	v_lshl_add_u64 v[150:151], s[6:7], 0, v[180:181]
	v_lshl_add_u64 v[154:155], s[6:7], 0, v[182:183]
	v_lshl_add_u64 v[158:159], s[6:7], 0, v[184:185]
	v_max_f32_e32 v250, v81, v81
	v_max_f32_e32 v251, v80, v80
	s_waitcnt lgkmcnt(8)
	v_mfma_f32_32x32x16_bf16 v[48:63], v[212:215], v[232:235], v[48:63]
	ds_read_b64_tr_b16 v[232:233], v193 offset:0x3200
	ds_read_b64_tr_b16 v[234:235], v193 offset:0x3a00
	v_max_f32_e32 v250, v251, v250
	v_max3_f32 v250, v250, v82, v83
	v_max3_f32 v250, v250, v84, v85
	v_max3_f32 v250, v250, v86, v87
	v_max3_f32 v250, v250, v88, v89
	s_waitcnt lgkmcnt(6)
	v_mfma_f32_32x32x16_bf16 v[32:47], v[162:165], v[216:219], v[32:47]
	ds_read_b64_tr_b16 v[216:217], v193 offset:0x400
	ds_read_b64_tr_b16 v[218:219], v193 offset:0xc00
	v_max3_f32 v250, v250, v90, v91
	v_max3_f32 v250, v250, v92, v93
	v_max3_f32 v250, v250, v94, v95
	v_max3_f32 v250, v250, v64, v65
	v_max3_f32 v250, v250, v66, v67
	s_waitcnt lgkmcnt(6)
	v_mfma_f32_32x32x16_bf16 v[32:47], v[166:169], v[220:223], v[32:47]
	ds_read_b64_tr_b16 v[220:221], v193 offset:0x1400
	ds_read_b64_tr_b16 v[222:223], v193 offset:0x1c00
	v_max3_f32 v250, v250, v68, v69
	v_max3_f32 v250, v250, v70, v71
	v_max3_f32 v250, v250, v72, v73
	v_max3_f32 v250, v250, v74, v75
	v_max3_f32 v250, v250, v76, v77
	global_load_dwordx4 v[146:149], v[146:147], off
	global_load_dwordx4 v[150:153], v[150:151], off
	global_load_dwordx4 v[154:157], v[154:155], off
	global_load_dwordx4 v[158:161], v[158:159], off
	s_waitcnt lgkmcnt(6)
	v_mfma_f32_32x32x16_bf16 v[32:47], v[170:173], v[224:227], v[32:47]
	ds_read_b64_tr_b16 v[224:225], v193 offset:0x2400
	ds_read_b64_tr_b16 v[226:227], v193 offset:0x2c00
	v_max3_f32 v250, v250, v78, v79
	v_mov_b32_e32 v251, v250
	s_nop 1
	v_permlane32_swap_b32_e32 v250, v251
	v_max_f32_e32 v251, v251, v251
	v_max_f32_e32 v250, v250, v250
	s_waitcnt lgkmcnt(6)
	v_mfma_f32_32x32x16_bf16 v[32:47], v[212:215], v[232:235], v[32:47]
	ds_read_b64_tr_b16 v[232:233], v193 offset:0x3400
	ds_read_b64_tr_b16 v[234:235], v193 offset:0x3c00
	v_max_f32_e32 v250, v250, v251
	v_sub_f32_e32 v251, v250, v174
	v_cmp_ge_f32_e32 vcc, s93, v251
	v_max_f32_e32 v251, v174, v174
	v_max_f32_e32 v250, v251, v250
	s_waitcnt lgkmcnt(6)
	v_mfma_f32_32x32x16_bf16 v[16:31], v[162:165], v[216:219], v[16:31]
	ds_read_b64_tr_b16 v[216:217], v193 offset:0x600
	ds_read_b64_tr_b16 v[218:219], v193 offset:0xe00
	v_sub_f32_e32 v251, v174, v250
	v_mul_f32_e32 v251, 0x3e0293ee, v251
	v_exp_f32_e32 v251, v251
	s_waitcnt lgkmcnt(6)
	v_mfma_f32_32x32x16_bf16 v[16:31], v[166:169], v[220:223], v[16:31]
	ds_read_b64_tr_b16 v[220:221], v193 offset:0x1600
	ds_read_b64_tr_b16 v[222:223], v193 offset:0x1e00
	s_waitcnt lgkmcnt(6)
	v_mfma_f32_32x32x16_bf16 v[16:31], v[170:173], v[224:227], v[16:31]
	ds_read_b64_tr_b16 v[224:225], v193 offset:0x2600
	ds_read_b64_tr_b16 v[226:227], v193 offset:0x2e00
	s_waitcnt lgkmcnt(6)
	v_mfma_f32_32x32x16_bf16 v[16:31], v[212:215], v[232:235], v[16:31]
	ds_read_b64_tr_b16 v[232:233], v193 offset:0x3600
	ds_read_b64_tr_b16 v[234:235], v193 offset:0x3e00
	s_waitcnt lgkmcnt(6)
	v_mfma_f32_32x32x16_bf16 v[0:15], v[162:165], v[216:219], v[0:15]
	s_waitcnt lgkmcnt(4)
	v_mfma_f32_32x32x16_bf16 v[0:15], v[166:169], v[220:223], v[0:15]
	s_waitcnt lgkmcnt(2)
	v_mfma_f32_32x32x16_bf16 v[0:15], v[170:173], v[224:227], v[0:15]
	s_waitcnt lgkmcnt(0)
	v_mfma_f32_32x32x16_bf16 v[0:15], v[212:215], v[232:235], v[0:15]
	s_cmp_eq_u64 vcc, exec
	s_cselect_b64 s[6:7], -1, 0
.Lgqa_joinA:
	s_barrier
	v_cndmask_b32_e64 v217, v251, 1.0, s[6:7]
	ds_write_b128 v195, v[128:131]
	ds_write_b128 v196, v[132:135]
	s_and_b64 vcc, exec, s[6:7]
	s_cbranch_vccz .Lresc_743

.Lgqa_loopA:
	ds_read_b128 v[236:239], v200 offset:49152
	ds_read_b128 v[240:243], v208 offset:49152
	ds_read_b128 v[244:247], v207 offset:49152
	ds_read_b128 v[248:251], v206 offset:49152
	s_add_i32 s6, s14, -3
	s_waitcnt lgkmcnt(3)
	v_mfma_f32_32x32x16_bf16 v[80:95], v[236:239], v[124:127], 0
	ds_read_b128 v[236:239], v205 offset:49152
	v_exp_f32_e32 v162, v162
	v_exp_f32_e32 v216, v216
	v_fma_f32 v158, v64, s92, v152
	v_fma_f32 v159, v65, s92, v152
	s_waitcnt lgkmcnt(3)
	v_mfma_f32_32x32x16_bf16 v[80:95], v[240:243], v[120:123], v[80:95]
	ds_read_b128 v[240:243], v204 offset:49152
	v_exp_f32_e32 v163, v163
	v_exp_f32_e32 v177, v177
	v_fma_f32 v156, v66, s92, v152
	v_fma_f32 v157, v67, s92, v152
	s_waitcnt lgkmcnt(3)
	v_mfma_f32_32x32x16_bf16 v[80:95], v[244:247], v[116:119], v[80:95]
	ds_read_b128 v[244:247], v202 offset:49152
	v_exp_f32_e32 v164, v164
	v_exp_f32_e32 v176, v176
	v_fma_f32 v150, v68, s92, v152
	v_fma_f32 v151, v69, s92, v152
	s_waitcnt lgkmcnt(3)
	v_mfma_f32_32x32x16_bf16 v[80:95], v[248:251], v[112:115], v[80:95]
	ds_read_b128 v[248:251], v201 offset:49152
	v_exp_f32_e32 v165, v165
	v_exp_f32_e32 v175, v175
	v_fma_f32 v148, v70, s92, v152
	v_fma_f32 v149, v71, s92, v152
	s_waitcnt lgkmcnt(3)
	v_mfma_f32_32x32x16_bf16 v[80:95], v[236:239], v[108:111], v[80:95]
	ds_read_b128 v[236:239], v200 offset:57344
	v_exp_f32_e32 v166, v166
	v_exp_f32_e32 v173, v173
	v_fma_f32 v146, v72, s92, v152
	v_fma_f32 v147, v73, s92, v152
	s_waitcnt lgkmcnt(3)
	v_mfma_f32_32x32x16_bf16 v[80:95], v[240:243], v[104:107], v[80:95]
	ds_read_b128 v[240:243], v208 offset:57344
	v_exp_f32_e32 v167, v167
	v_exp_f32_e32 v172, v172
	v_fma_f32 v160, v74, s92, v152
	v_fma_f32 v161, v75, s92, v152
	s_waitcnt lgkmcnt(3)
	v_mfma_f32_32x32x16_bf16 v[80:95], v[244:247], v[100:103], v[80:95]
	ds_read_b128 v[244:247], v207 offset:57344
	v_exp_f32_e32 v168, v168
	v_exp_f32_e32 v171, v171
	v_fma_f32 v154, v76, s92, v152
	v_fma_f32 v155, v77, s92, v152
	s_waitcnt lgkmcnt(3)
	v_mfma_f32_32x32x16_bf16 v[80:95], v[248:251], v[96:99], v[80:95]
	ds_read_b128 v[248:251], v206 offset:57344
	v_exp_f32_e32 v169, v169
	v_exp_f32_e32 v170, v170
	v_fma_f32 v153, v79, s92, v152
	v_fma_f32 v152, v78, s92, v152
	s_waitcnt lgkmcnt(3)
	v_mfma_f32_32x32x16_bf16 v[64:79], v[236:239], v[124:127], 0
	ds_read_b128 v[236:239], v205 offset:57344
	v_exp_f32_e32 v158, v158
	v_exp_f32_e32 v159, v159
	v_add_f32_e32 v210, 0, v162
	s_waitcnt lgkmcnt(3)
	v_mfma_f32_32x32x16_bf16 v[64:79], v[240:243], v[120:123], v[64:79]
	ds_read_b128 v[240:243], v204 offset:57344
	v_exp_f32_e32 v156, v156
	v_exp_f32_e32 v157, v157
	v_add_f32_e32 v210, v216, v210
	s_waitcnt lgkmcnt(3)
	v_mfma_f32_32x32x16_bf16 v[64:79], v[244:247], v[116:119], v[64:79]
	ds_read_b128 v[244:247], v202 offset:57344
	v_exp_f32_e32 v150, v150
	v_exp_f32_e32 v151, v151
	v_add_f32_e32 v210, v163, v210
	s_waitcnt lgkmcnt(3)
	v_mfma_f32_32x32x16_bf16 v[64:79], v[248:251], v[112:115], v[64:79]
	ds_read_b128 v[248:251], v201 offset:57344
	v_exp_f32_e32 v148, v148
	v_exp_f32_e32 v149, v149
	v_add_f32_e32 v210, v177, v210
	s_waitcnt lgkmcnt(3)
	v_mfma_f32_32x32x16_bf16 v[64:79], v[236:239], v[108:111], v[64:79]
	v_exp_f32_e32 v146, v146
	v_exp_f32_e32 v147, v147
	v_add_f32_e32 v210, v164, v210
	s_waitcnt lgkmcnt(2)
	v_mfma_f32_32x32x16_bf16 v[64:79], v[240:243], v[104:107], v[64:79]
	v_exp_f32_e32 v160, v160
	v_exp_f32_e32 v161, v161
	v_add_f32_e32 v210, v176, v210
	s_waitcnt lgkmcnt(1)
	v_mfma_f32_32x32x16_bf16 v[64:79], v[244:247], v[100:103], v[64:79]
	v_exp_f32_e32 v154, v154
	v_exp_f32_e32 v155, v155
	v_add_f32_e32 v210, v165, v210
	s_waitcnt lgkmcnt(0)
	v_mfma_f32_32x32x16_bf16 v[64:79], v[248:251], v[96:99], v[64:79]
	v_exp_f32_e32 v152, v152
	v_exp_f32_e32 v153, v153
	v_add_f32_e32 v210, v175, v210
	s_waitcnt vmcnt(0)
	ds_write_b128 v198, v[136:139] offset:32768
	ds_write_b128 v199, v[140:143] offset:32768
	s_sub_i32 s7, s8, 64
	s_cmp_lt_u32 s6, 2
	s_cselect_b32 s6, s15, s7
	s_ashr_i32 s7, s6, 31
	s_mul_hi_u32 s100, s6, s40
	s_mul_i32 s101, s6, s41
	s_add_u32 s100, s100, s101
	s_mul_i32 s101, s7, s40
	s_add_u32 s100, s100, s101
	s_mul_i32 s6, s6, s40
	s_mov_b32 s7, s100
	s_lshl_b64 s[6:7], s[6:7], 1
	v_cvt_pk_bf16_f32 v162, v162, v216
	v_cvt_pk_bf16_f32 v163, v163, v177
	v_cvt_pk_bf16_f32 v164, v164, v176
	v_cvt_pk_bf16_f32 v165, v165, v175
	s_nop 0
	v_permlane32_swap_b32_e32 v162, v164
	v_permlane32_swap_b32_e32 v163, v165
	ds_read_b64_tr_b16 v[216:217], v193 offset:0
	ds_read_b64_tr_b16 v[218:219], v193 offset:0x800
	s_waitcnt lgkmcnt(0)
	v_mfma_f32_32x32x16_bf16 v[48:63], v[162:165], v[216:219], v[48:63]
	ds_read_b64_tr_b16 v[220:221], v193 offset:0x1000
	ds_read_b64_tr_b16 v[222:223], v193 offset:0x1800
	ds_read_b64_tr_b16 v[224:225], v193 offset:0x2000
	ds_read_b64_tr_b16 v[226:227], v193 offset:0x2800
	ds_read_b64_tr_b16 v[232:233], v193 offset:0x3000
	ds_read_b64_tr_b16 v[234:235], v193 offset:0x3800
	ds_read_b64_tr_b16 v[216:217], v193 offset:0x200
	ds_read_b64_tr_b16 v[218:219], v193 offset:0xa00
	v_add_f32_e32 v210, v166, v210
	v_add_f32_e32 v210, v173, v210
	v_add_f32_e32 v210, v167, v210
	v_add_f32_e32 v210, v172, v210
	v_add_f32_e32 v210, v168, v210
	v_add_f32_e32 v210, v171, v210
	v_add_f32_e32 v210, v169, v210
	v_cvt_pk_bf16_f32 v166, v166, v173
	v_cvt_pk_bf16_f32 v167, v167, v172
	v_cvt_pk_bf16_f32 v168, v168, v171
	v_cvt_pk_bf16_f32 v169, v169, v170
	s_nop 0
	v_permlane32_swap_b32_e32 v166, v168
	v_permlane32_swap_b32_e32 v167, v169
	s_waitcnt lgkmcnt(6)
	s_nop 0
	v_mfma_f32_32x32x16_bf16 v[48:63], v[166:169], v[220:223], v[48:63]
	ds_read_b64_tr_b16 v[220:221], v193 offset:0x1200
	ds_read_b64_tr_b16 v[222:223], v193 offset:0x1a00
	v_add_f32_e32 v210, v170, v210
	v_add_f32_e32 v210, v158, v210
	v_add_f32_e32 v210, v159, v210
	v_add_f32_e32 v210, v156, v210
	v_add_f32_e32 v210, v157, v210
	v_cvt_pk_bf16_f32 v170, v158, v159
	v_cvt_pk_bf16_f32 v171, v156, v157
	v_cvt_pk_bf16_f32 v172, v150, v151
	v_cvt_pk_bf16_f32 v173, v148, v149
	s_nop 0
	v_permlane32_swap_b32_e32 v170, v172
	v_permlane32_swap_b32_e32 v171, v173
	s_waitcnt lgkmcnt(6)
	s_nop 0
	v_mfma_f32_32x32x16_bf16 v[48:63], v[170:173], v[224:227], v[48:63]
	ds_read_b64_tr_b16 v[224:225], v193 offset:0x2200
	ds_read_b64_tr_b16 v[226:227], v193 offset:0x2a00
	v_add_f32_e32 v210, v150, v210
	v_add_f32_e32 v210, v151, v210
	v_add_f32_e32 v210, v148, v210
	v_add_f32_e32 v210, v149, v210
	v_add_f32_e32 v210, v146, v210
	v_cvt_pk_bf16_f32 v212, v146, v147
	v_cvt_pk_bf16_f32 v213, v160, v161
	v_cvt_pk_bf16_f32 v214, v154, v155
	v_cvt_pk_bf16_f32 v215, v152, v153
	s_nop 0
	v_permlane32_swap_b32_e32 v212, v214
	v_permlane32_swap_b32_e32 v213, v215
	s_waitcnt lgkmcnt(6)
	s_nop 0
	v_mfma_f32_32x32x16_bf16 v[48:63], v[212:215], v[232:235], v[48:63]
	ds_read_b64_tr_b16 v[232:233], v193 offset:0x3200
	ds_read_b64_tr_b16 v[234:235], v193 offset:0x3a00
	v_add_f32_e32 v210, v147, v210
	v_add_f32_e32 v210, v160, v210
	v_add_f32_e32 v210, v161, v210
	v_add_f32_e32 v210, v154, v210
	v_add_f32_e32 v210, v155, v210
	s_waitcnt lgkmcnt(6)
	v_mfma_f32_32x32x16_bf16 v[32:47], v[162:165], v[216:219], v[32:47]
	ds_read_b64_tr_b16 v[216:217], v193 offset:0x400
	ds_read_b64_tr_b16 v[218:219], v193 offset:0xc00
	v_add_f32_e32 v210, v152, v210
	v_add_f32_e32 v210, v153, v210
	v_mov_b32_e32 v211, v210
	s_nop 1
	v_permlane32_swap_b32_e32 v210, v211
	v_lshl_add_u64 v[146:147], s[6:7], 0, v[178:179]
	s_waitcnt lgkmcnt(6)
	v_mfma_f32_32x32x16_bf16 v[32:47], v[166:169], v[220:223], v[32:47]
	ds_read_b64_tr_b16 v[220:221], v193 offset:0x1400
	ds_read_b64_tr_b16 v[222:223], v193 offset:0x1c00
	v_lshl_add_u64 v[150:151], s[6:7], 0, v[180:181]
	v_lshl_add_u64 v[154:155], s[6:7], 0, v[182:183]
	v_lshl_add_u64 v[158:159], s[6:7], 0, v[184:185]
	v_max_f32_e32 v250, v81, v81
	v_max_f32_e32 v251, v80, v80
	global_load_dwordx4 v[146:149], v[146:147], off
	global_load_dwordx4 v[150:153], v[150:151], off
	global_load_dwordx4 v[154:157], v[154:155], off
	global_load_dwordx4 v[158:161], v[158:159], off
	s_waitcnt lgkmcnt(6)
	v_mfma_f32_32x32x16_bf16 v[32:47], v[170:173], v[224:227], v[32:47]
	ds_read_b64_tr_b16 v[224:225], v193 offset:0x2400
	ds_read_b64_tr_b16 v[226:227], v193 offset:0x2c00
	v_max_f32_e32 v250, v251, v250
	v_max3_f32 v250, v250, v82, v83
	v_max3_f32 v250, v250, v84, v85
	v_max3_f32 v250, v250, v86, v87
	v_max3_f32 v250, v250, v88, v89
	s_waitcnt lgkmcnt(6)
	v_mfma_f32_32x32x16_bf16 v[32:47], v[212:215], v[232:235], v[32:47]
	ds_read_b64_tr_b16 v[232:233], v193 offset:0x3400
	ds_read_b64_tr_b16 v[234:235], v193 offset:0x3c00
	v_max3_f32 v250, v250, v90, v91
	v_max3_f32 v250, v250, v92, v93
	v_max3_f32 v250, v250, v94, v95
	v_max3_f32 v250, v250, v64, v65
	v_max3_f32 v250, v250, v66, v67
	s_waitcnt lgkmcnt(6)
	v_mfma_f32_32x32x16_bf16 v[16:31], v[162:165], v[216:219], v[16:31]
	ds_read_b64_tr_b16 v[216:217], v193 offset:0x600
	ds_read_b64_tr_b16 v[218:219], v193 offset:0xe00
	v_max3_f32 v250, v250, v68, v69
	v_max3_f32 v250, v250, v70, v71
	v_max3_f32 v250, v250, v72, v73
	v_max3_f32 v250, v250, v74, v75
	v_max3_f32 v250, v250, v76, v77
	s_waitcnt lgkmcnt(6)
	v_mfma_f32_32x32x16_bf16 v[16:31], v[166:169], v[220:223], v[16:31]
	ds_read_b64_tr_b16 v[220:221], v193 offset:0x1600
	ds_read_b64_tr_b16 v[222:223], v193 offset:0x1e00
	v_max3_f32 v250, v250, v78, v79
	v_mov_b32_e32 v251, v250
	s_nop 1
	v_permlane32_swap_b32_e32 v250, v251
	v_max_f32_e32 v251, v251, v251
	v_max_f32_e32 v250, v250, v250
	s_waitcnt lgkmcnt(6)
	v_mfma_f32_32x32x16_bf16 v[16:31], v[170:173], v[224:227], v[16:31]
	ds_read_b64_tr_b16 v[224:225], v193 offset:0x2600
	ds_read_b64_tr_b16 v[226:227], v193 offset:0x2e00
	v_max_f32_e32 v250, v250, v251
	v_sub_f32_e32 v251, v250, v174
	v_cmp_ge_f32_e32 vcc, s93, v251
	v_max_f32_e32 v251, v174, v174
	v_max_f32_e32 v250, v251, v250
	s_waitcnt lgkmcnt(6)
	v_mfma_f32_32x32x16_bf16 v[16:31], v[212:215], v[232:235], v[16:31]
	ds_read_b64_tr_b16 v[232:233], v193 offset:0x3600
	ds_read_b64_tr_b16 v[234:235], v193 offset:0x3e00
	v_sub_f32_e32 v251, v174, v250
	v_mul_f32_e32 v251, 0x3e0293ee, v251
	v_exp_f32_e32 v251, v251
	s_waitcnt lgkmcnt(6)
	v_mfma_f32_32x32x16_bf16 v[0:15], v[162:165], v[216:219], v[0:15]
	s_waitcnt lgkmcnt(4)
	v_mfma_f32_32x32x16_bf16 v[0:15], v[166:169], v[220:223], v[0:15]
	s_waitcnt lgkmcnt(2)
	v_mfma_f32_32x32x16_bf16 v[0:15], v[170:173], v[224:227], v[0:15]
	s_waitcnt lgkmcnt(0)
	v_mfma_f32_32x32x16_bf16 v[0:15], v[212:215], v[232:235], v[0:15]
	s_cmp_eq_u64 vcc, exec
	s_cselect_b64 s[6:7], -1, 0
	s_branch .Lgqa_joinA

.LBB0_761:
	v_mbcnt_lo_u32_b32 v0, -1, 0
	v_mbcnt_hi_u32_b32 v0, -1, v0
	s_add_i32 s4, 0, 0x10000
	v_add_u32_e32 v0, s66, v0
	s_cmp_lg_u32 0, -1
	v_ashrrev_i32_e32 v178, 6, v0
	v_and_b32_e32 v179, 31, v0
	v_lshlrev_b32_e32 v175, 5, v178
	v_or_b32_e32 v2, s86, v179
	v_add_u32_e32 v2, v2, v175
	v_and_b32_e32 v1, 0x3fffffc0, v0
	v_ashrrev_i32_e32 v3, 31, v2
	v_lshl_add_u32 v180, v1, 2, s4
	v_mul_lo_u32 v4, s40, v3
	v_mul_lo_u32 v5, s41, v2
	v_mad_u64_u32 v[2:3], s[4:5], s40, v2, 0
	v_add3_u32 v3, v3, v4, v5
	v_bfe_u32 v177, v0, 5, 1
	v_lshlrev_b64 v[2:3], 1, v[2:3]
	v_lshl_add_u64 v[4:5], s[88:89], 0, v[2:3]
	v_lshlrev_b32_e32 v144, 4, v177
	v_lshl_add_u64 v[2:3], s[72:73], 0, v[2:3]
	v_lshl_add_u64 v[4:5], v[4:5], 0, v[144:145]
	v_lshl_add_u64 v[6:7], v[2:3], 0, v[144:145]
	global_load_dwordx4 v[124:127], v[4:5], off
	global_load_dwordx4 v[120:123], v[4:5], off offset:32
	global_load_dwordx4 v[116:119], v[4:5], off offset:64
	global_load_dwordx4 v[112:115], v[4:5], off offset:96
	global_load_dwordx4 v[108:111], v[4:5], off offset:128
	global_load_dwordx4 v[104:107], v[4:5], off offset:160
	global_load_dwordx4 v[100:103], v[4:5], off offset:192
	global_load_dwordx4 v[96:99], v[4:5], off offset:224
	v_and_b32_e32 v174, 63, v0
	global_load_dwordx4 v[2:5], v[6:7], off
	v_lshl_add_u32 v1, v178, 12, s53
	v_lshlrev_b32_e32 v8, 4, v174
	v_add_u32_e32 v182, v1, v8
	v_ashrrev_i32_e32 v162, 4, v0
	v_lshlrev_b32_e32 v56, 3, v0
	v_and_b32_e32 v1, 0x78, v56
	v_lshlrev_b32_e32 v48, 1, v1
	v_and_b32_e32 v1, 48, v48
	v_add_u32_e32 v23, 32, v162
	v_ashrrev_i32_e32 v163, 31, v162
	s_cselect_b32 s6, 0, 0
	s_ashr_i32 s83, s82, 31
	v_lshl_add_u64 v[166:167], v[162:163], 0, 32
	v_ashrrev_i32_e32 v164, 3, v0
	v_ashrrev_i32_e32 v165, 31, v164
	v_lshl_add_u64 v[18:19], v[164:165], 0, s[82:83]
	v_mov_b64_e32 v[52:53], s[0:1]
	v_mad_u64_u32 v[20:21], s[4:5], v18, s3, v[52:53]
	v_lshlrev_b32_e32 v176, 4, v0
	v_mov_b32_e32 v49, v145
	v_mad_i32_i24 v21, v19, s3, v21
	v_and_b32_e32 v50, 0x70, v176
	v_mov_b32_e32 v51, v145
	v_lshl_add_u64 v[18:19], v[20:21], 0, v[50:51]
	global_load_dwordx4 v[18:21], v[18:19], off
	v_lshlrev_b32_e32 v57, 8, v179
	v_or_b32_e32 v68, 32, v144
	v_bitop3_b32 v58, v68, v57, v50 bitop3:0xde
	v_add_u32_e32 v191, 0, v58
	v_or_b32_e32 v69, 64, v144
	v_or_b32_e32 v70, 0x60, v144
	v_lshlrev_b32_e32 v71, 7, v179
	v_and_b32_e32 v72, 0x70, v56
	v_bitop3_b32 v198, v144, v71, v72 bitop3:0xde
	v_bitop3_b32 v200, v68, v71, v72 bitop3:0xde
	v_bitop3_b32 v202, v69, v71, v72 bitop3:0xde
	v_bitop3_b32 v204, v70, v71, v72 bitop3:0xde
	s_mov_b32 s8, 0
	s_mov_b32 s9, s8
	s_mov_b32 s10, s8
	s_mov_b32 s11, s8
	s_mov_b32 s12, s8
	s_mov_b32 s13, s8
	s_mov_b32 s14, s8
	s_mov_b32 s15, s8
	s_mov_b32 s16, s8
	s_mov_b32 s17, s8
	s_mov_b32 s18, s8
	s_mov_b32 s19, s8
	s_mov_b32 s20, s8
	s_mov_b32 s21, s8
	s_mov_b32 s22, s8
	s_mov_b32 s23, s8
	v_lshl_add_u64 v[168:169], s[80:81], 0, v[48:49]
	v_lshl_add_u64 v[170:171], s[78:79], 0, v[48:49]
	v_lshl_add_u64 v[172:173], s[0:1], 0, v[50:51]
	s_mov_b32 s24, 2
	v_lshl_add_u32 v183, v179, 2, v180
	v_mov_b32_e32 v197, 0
	s_waitcnt vmcnt(0)
	ds_write_b128 v182, v[2:5]
	global_load_dwordx4 v[2:5], v[6:7], off offset:32
	s_waitcnt vmcnt(0)
	ds_write_b128 v182, v[2:5] offset:1024
	global_load_dwordx4 v[2:5], v[6:7], off offset:64
	s_waitcnt vmcnt(0)
	ds_write_b128 v182, v[2:5] offset:2048
	global_load_dwordx4 v[2:5], v[6:7], off offset:96
	v_lshl_add_u64 v[6:7], v[166:167], 0, s[82:83]
	v_mul_lo_u32 v9, v6, s41
	s_waitcnt vmcnt(0)
	ds_write_b128 v182, v[2:5] offset:3072
	v_and_b32_e32 v2, 0xfffff0, v162
	v_lshlrev_b32_e32 v3, 1, v162
	v_and_or_b32 v2, v3, 8, v2
	v_lshrrev_b32_e32 v3, 1, v162
	v_lshrrev_b32_e32 v2, 1, v2
	v_bfe_u32 v4, v56, 5, 2
	v_and_b32_e32 v5, 3, v162
	v_or_b32_e32 v2, v2, v4
	v_and_or_b32 v3, v3, 4, v5
	v_lshlrev_b32_e32 v2, 9, v2
	v_lshlrev_b32_e32 v3, 6, v3
	v_or3_b32 v22, v2, v3, v1
	v_and_b32_e32 v2, 0xfffff0, v23
	v_lshlrev_b32_e32 v5, 1, v23
	v_and_or_b32 v2, v5, 8, v2
	v_lshrrev_b32_e32 v2, 1, v2
	v_or_b32_e32 v2, v2, v4
	v_lshlrev_b32_e32 v2, 9, v2
	v_or3_b32 v1, v2, v3, v1
	v_lshlrev_b32_e32 v2, 3, v174
	v_and_b32_e32 v3, 0xc0, v8
	v_lshlrev_b32_e32 v4, 1, v0
	v_and_or_b32 v3, v2, 24, v3
	v_and_b32_e32 v4, 32, v4
	v_and_b32_e32 v2, 0x100, v2
	v_or3_b32 v54, v3, v4, v2
	v_lshl_add_u64 v[2:3], v[162:163], 0, s[82:83]
	v_mul_lo_u32 v4, v3, s40
	v_mul_lo_u32 v5, v2, s41
	v_mad_u64_u32 v[2:3], s[4:5], v2, s40, 0
	v_mul_lo_u32 v8, v7, s40
	v_mad_u64_u32 v[6:7], s[4:5], v6, s40, 0
	v_add3_u32 v3, v3, v5, v4
	v_add3_u32 v7, v7, v9, v8
	v_lshlrev_b64 v[10:11], 1, v[2:3]
	v_lshlrev_b64 v[14:15], 1, v[6:7]
	v_lshl_add_u64 v[2:3], s[80:81], 0, v[10:11]
	v_lshl_add_u64 v[6:7], s[80:81], 0, v[14:15]
	v_lshl_add_u64 v[10:11], s[78:79], 0, v[10:11]
	v_lshl_add_u64 v[14:15], s[78:79], 0, v[14:15]
	v_lshl_add_u64 v[2:3], v[2:3], 0, v[48:49]
	v_lshl_add_u64 v[6:7], v[6:7], 0, v[48:49]
	v_lshl_add_u64 v[10:11], v[10:11], 0, v[48:49]
	v_lshl_add_u64 v[14:15], v[14:15], 0, v[48:49]
	global_load_dwordx4 v[2:5], v[2:3], off
	v_add_u32_e32 v186, 0, v1
	global_load_dwordx4 v[6:9], v[6:7], off
	v_lshlrev_b32_e32 v1, 8, v162
	global_load_dwordx4 v[10:13], v[10:11], off
	v_and_b32_e32 v0, 0x70, v0
	global_load_dwordx4 v[14:17], v[14:15], off
	v_bitop3_b32 v1, v48, v1, v0 bitop3:0xde
	v_add_u32_e32 v187, 0, v1
	v_lshlrev_b32_e32 v1, 8, v23
	v_bitop3_b32 v1, v48, v1, v0 bitop3:0xde
	v_add_u32_e32 v188, 0, v1
	v_lshlrev_b32_e32 v1, 7, v164
	v_bitop3_b32 v55, v50, v1, v0 bitop3:0xde
	s_add_i32 s4, 0, 0x10800
	v_add_u32_e32 v185, 0, v22
	v_add_u32_e32 v0, s4, v55
	s_waitcnt vmcnt(0)
	v_add_u32_e32 v199, s4, v198
	v_add_u32_e32 v201, s4, v200
	v_add_u32_e32 v203, s4, v202
	v_add_u32_e32 v205, s4, v204
	v_add_u32_e32 v208, 0, v55
	v_add_u32_e32 v181, s6, v54
	v_add_u32_e32 v209, 0x12800, v208
	s_waitcnt vmcnt(3)
	ds_write_b128 v185, v[2:5]
	s_waitcnt vmcnt(2)
	ds_write_b128 v186, v[6:9]
	s_waitcnt vmcnt(1)
	ds_write_b128 v187, v[10:13] offset:32768
	s_waitcnt vmcnt(0)
	ds_write_b128 v188, v[14:17] offset:32768
	ds_write_b128 v0, v[18:21]
	v_bitop3_b32 v0, v144, v57, v50 bitop3:0xde
	v_add_u32_e32 v189, 0, v0
	s_waitcnt lgkmcnt(0)
	s_barrier
	ds_read_b128 v[16:19], v189 offset:32768
	ds_read_b128 v[20:23], v189 offset:40960
	s_waitcnt lgkmcnt(1)
	v_mfma_f32_32x32x16_bf16 v[32:47], v[16:19], v[124:127], 0
	ds_read_b128 v[58:61], v191 offset:32768
	ds_read_b128 v[62:65], v191 offset:40960
	v_mov_b64_e32 v[0:1], s[8:9]
	v_mov_b64_e32 v[2:3], s[10:11]
	v_mov_b64_e32 v[4:5], s[12:13]
	v_mov_b64_e32 v[6:7], s[14:15]
	v_mov_b64_e32 v[8:9], s[16:17]
	v_mov_b64_e32 v[10:11], s[18:19]
	s_waitcnt lgkmcnt(2)
	v_mfma_f32_32x32x16_bf16 v[16:31], v[20:23], v[124:127], 0
	v_mov_b64_e32 v[12:13], s[20:21]
	v_mov_b64_e32 v[14:15], s[22:23]
	s_waitcnt lgkmcnt(1)
	v_mfma_f32_32x32x16_bf16 v[32:47], v[58:61], v[120:123], v[32:47]
	v_bitop3_b32 v58, v69, v57, v50 bitop3:0xde
	v_add_u32_e32 v193, 0, v58
	s_waitcnt lgkmcnt(0)
	v_mfma_f32_32x32x16_bf16 v[16:31], v[62:65], v[120:123], v[16:31]
	ds_read_b128 v[58:61], v193 offset:32768
	ds_read_b128 v[62:65], v193 offset:40960
	s_waitcnt lgkmcnt(1)
	v_mfma_f32_32x32x16_bf16 v[32:47], v[58:61], v[116:119], v[32:47]
	v_bitop3_b32 v58, v70, v57, v50 bitop3:0xde
	v_add_u32_e32 v195, 0, v58
	s_waitcnt lgkmcnt(0)
	v_mfma_f32_32x32x16_bf16 v[16:31], v[62:65], v[116:119], v[16:31]
	ds_read_b128 v[58:61], v195 offset:32768
	ds_read_b128 v[62:65], v195 offset:40960
	s_waitcnt lgkmcnt(1)
	v_mfma_f32_32x32x16_bf16 v[32:47], v[58:61], v[112:115], v[32:47]
	v_or_b32_e32 v58, 0x80, v144
	v_bitop3_b32 v58, v58, v57, v50 bitop3:0xde
	v_add_u32_e32 v196, 0, v58
	s_waitcnt lgkmcnt(0)
	v_mfma_f32_32x32x16_bf16 v[16:31], v[62:65], v[112:115], v[16:31]
	ds_read_b128 v[58:61], v196 offset:32768
	ds_read_b128 v[62:65], v196 offset:40960
	s_waitcnt lgkmcnt(1)
	v_mfma_f32_32x32x16_bf16 v[32:47], v[58:61], v[108:111], v[32:47]
	v_or_b32_e32 v58, 0xa0, v144
	v_bitop3_b32 v58, v58, v57, v50 bitop3:0xde
	v_add_u32_e32 v194, 0, v58
	s_waitcnt lgkmcnt(0)
	v_mfma_f32_32x32x16_bf16 v[16:31], v[62:65], v[108:111], v[16:31]
	ds_read_b128 v[58:61], v194 offset:32768
	ds_read_b128 v[62:65], v194 offset:40960
	s_waitcnt lgkmcnt(1)
	v_mfma_f32_32x32x16_bf16 v[32:47], v[58:61], v[104:107], v[32:47]
	v_or_b32_e32 v58, 0xc0, v144
	v_bitop3_b32 v58, v58, v57, v50 bitop3:0xde
	v_add_u32_e32 v192, 0, v58
	s_waitcnt lgkmcnt(0)
	v_mfma_f32_32x32x16_bf16 v[16:31], v[62:65], v[104:107], v[16:31]
	ds_read_b128 v[58:61], v192 offset:32768
	ds_read_b128 v[62:65], v192 offset:40960
	s_waitcnt lgkmcnt(1)
	v_mfma_f32_32x32x16_bf16 v[32:47], v[58:61], v[100:103], v[32:47]
	v_or_b32_e32 v58, 0xe0, v144
	v_bitop3_b32 v57, v58, v57, v50 bitop3:0xde
	v_add_u32_e32 v190, 0, v57
	s_waitcnt lgkmcnt(0)
	v_mfma_f32_32x32x16_bf16 v[16:31], v[62:65], v[100:103], v[16:31]
	ds_read_b128 v[58:61], v190 offset:32768
	ds_read_b128 v[62:65], v190 offset:40960
	s_waitcnt lgkmcnt(1)
	v_mfma_f32_32x32x16_bf16 v[32:47], v[58:61], v[96:99], v[32:47]
	s_waitcnt lgkmcnt(0)
	v_mfma_f32_32x32x16_bf16 v[16:31], v[62:65], v[96:99], v[16:31]
	ds_read_b128 v[56:59], v199
	ds_read_b128 v[60:63], v199 offset:4096
	ds_read_b128 v[64:67], v182
	s_waitcnt lgkmcnt(0)
	v_mfma_f32_32x32x16_bf16 v[32:47], v[56:59], v[64:67], v[32:47]
	v_mfma_f32_32x32x16_bf16 v[16:31], v[60:63], v[64:67], v[16:31]
	ds_read_b128 v[56:59], v201
	ds_read_b128 v[60:63], v201 offset:4096
	ds_read_b128 v[64:67], v182 offset:1024
	s_waitcnt lgkmcnt(0)
	v_mfma_f32_32x32x16_bf16 v[32:47], v[56:59], v[64:67], v[32:47]
	v_mfma_f32_32x32x16_bf16 v[16:31], v[60:63], v[64:67], v[16:31]
	ds_read_b128 v[56:59], v203
	ds_read_b128 v[60:63], v203 offset:4096
	ds_read_b128 v[64:67], v182 offset:2048
	s_waitcnt lgkmcnt(0)
	v_mfma_f32_32x32x16_bf16 v[32:47], v[56:59], v[64:67], v[32:47]
	v_mfma_f32_32x32x16_bf16 v[16:31], v[60:63], v[64:67], v[16:31]
	ds_read_b128 v[56:59], v205
	ds_read_b128 v[60:63], v205 offset:4096
	ds_read_b128 v[64:67], v182 offset:3072
	s_waitcnt lgkmcnt(0)
	v_mfma_f32_32x32x16_bf16 v[32:47], v[56:59], v[64:67], v[32:47]
	v_mfma_f32_32x32x16_bf16 v[16:31], v[60:63], v[64:67], v[16:31]
	s_nop 10
	v_max_f32_e32 v56, v33, v33
	v_max_f32_e32 v57, v32, v32
	v_max_f32_e32 v56, v57, v56
	v_max3_f32 v56, v56, v34, v35
	v_max3_f32 v56, v56, v36, v37
	v_max3_f32 v56, v56, v38, v39
	v_max3_f32 v56, v56, v40, v41
	v_max3_f32 v56, v56, v42, v43
	v_max3_f32 v56, v56, v44, v45
	v_max3_f32 v56, v56, v46, v47
	v_max3_f32 v56, v56, v16, v17
	v_max3_f32 v56, v56, v18, v19
	v_max3_f32 v56, v56, v20, v21
	v_max3_f32 v56, v56, v22, v23
	v_max3_f32 v56, v56, v24, v25
	v_max3_f32 v56, v56, v26, v27
	v_max3_f32 v56, v56, v28, v29
	v_max3_f32 v56, v56, v30, v31
	v_mov_b32_e32 v57, v56
	s_nop 1
	v_permlane32_swap_b32_e32 v56, v57
	v_max_f32_e32 v57, v57, v57
	v_max_f32_e32 v56, v56, v56
	v_max_f32_e32 v56, v56, v57
	v_add_f32_e32 v57, 0x7149f2ca, v56
	v_max_f32_e32 v56, 0xf149f2ca, v56
	v_cmp_ge_f32_e32 vcc, s94, v57
	v_sub_f32_e32 v57, 0xf149f2ca, v56
	v_mul_f32_e32 v57, 0x3dd53b94, v57
	s_cmp_eq_u64 vcc, exec
	v_exp_f32_e32 v57, v57
	s_cselect_b64 vcc, -1, 0
	v_cndmask_b32_e32 v207, v56, v231, vcc
	v_mul_f32_e32 v56, 0xbdd53b94, v207
	v_cndmask_b32_e64 v206, v57, 1.0, vcc
	v_mov_b32_e32 v57, v56
	s_add_i32 s4, s46, 0x4040
	v_fmac_f32_e32 v57, 0x3dd53b94, v47
	s_ashr_i32 s5, s4, 31
	v_fma_f32 v140, v16, s76, v56
	v_fma_f32 v141, v17, s76, v56
	v_lshl_add_u64 v[16:17], v[162:163], 0, s[4:5]
	v_fmamk_f32 v32, v32, 0x3dd53b94, v56
	v_fmamk_f32 v33, v33, 0x3dd53b94, v56
	v_fma_f32 v132, v20, s76, v56
	v_fma_f32 v133, v21, s76, v56
	v_fma_f32 v138, v18, s76, v56
	v_fma_f32 v139, v19, s76, v56
	v_mul_lo_u32 v18, v17, s40
	v_mul_lo_u32 v19, v16, s41
	v_mad_u64_u32 v[16:17], s[10:11], v16, s40, 0
	v_lshl_add_u64 v[20:21], v[166:167], 0, s[4:5]
	v_fmamk_f32 v34, v34, 0x3dd53b94, v56
	v_fmamk_f32 v35, v35, 0x3dd53b94, v56
	v_fma_f32 v130, v22, s76, v56
	v_fma_f32 v131, v23, s76, v56
	v_exp_f32_e32 v159, v32
	v_exp_f32_e32 v161, v33
	v_add3_u32 v17, v17, v19, v18
	v_mul_lo_u32 v22, v21, s40
	v_mul_lo_u32 v23, v20, s41
	v_mad_u64_u32 v[20:21], s[10:11], v20, s40, 0
	v_lshl_add_u64 v[32:33], v[164:165], 0, s[4:5]
	v_fma_f32 v128, v24, s76, v56
	v_fma_f32 v129, v25, s76, v56
	v_exp_f32_e32 v157, v34
	v_exp_f32_e32 v160, v35
	v_lshlrev_b64 v[24:25], 1, v[16:17]
	v_add3_u32 v21, v21, v23, v22
	v_mad_u64_u32 v[34:35], s[4:5], v32, s3, v[52:53]
	v_fma_f32 v136, v28, s76, v56
	v_fma_f32 v137, v29, s76, v56
	v_lshl_add_u64 v[16:17], s[80:81], 0, v[24:25]
	v_lshlrev_b64 v[28:29], 1, v[20:21]
	v_mad_i32_i24 v35, v33, s3, v35
	v_lshl_add_u64 v[16:17], v[16:17], 0, v[48:49]
	v_lshl_add_u64 v[20:21], s[80:81], 0, v[28:29]
	v_lshl_add_u64 v[32:33], v[34:35], 0, v[50:51]
	global_load_dwordx4 v[16:19], v[16:17], off
	v_lshl_add_u64 v[20:21], v[20:21], 0, v[48:49]
	v_lshl_add_u64 v[24:25], s[78:79], 0, v[24:25]
	global_load_dwordx4 v[32:35], v[32:33], off
	v_lshl_add_u64 v[24:25], v[24:25], 0, v[48:49]
	global_load_dwordx4 v[20:23], v[20:21], off
	v_lshl_add_u64 v[28:29], s[78:79], 0, v[28:29]
	v_fma_f32 v142, v26, s76, v56
	v_fma_f32 v143, v27, s76, v56
	global_load_dwordx4 v[24:27], v[24:25], off
	v_lshl_add_u64 v[28:29], v[28:29], 0, v[48:49]
	v_fma_f32 v134, v30, s76, v56
	v_fma_f32 v135, v31, s76, v56
	global_load_dwordx4 v[28:31], v[28:29], off
	v_fmamk_f32 v36, v36, 0x3dd53b94, v56
	v_fmamk_f32 v37, v37, 0x3dd53b94, v56
	v_fmamk_f32 v38, v38, 0x3dd53b94, v56
	v_fmamk_f32 v39, v39, 0x3dd53b94, v56
	v_fmamk_f32 v40, v40, 0x3dd53b94, v56
	v_fmamk_f32 v41, v41, 0x3dd53b94, v56
	v_fmamk_f32 v42, v42, 0x3dd53b94, v56
	v_fmamk_f32 v43, v43, 0x3dd53b94, v56
	v_fmamk_f32 v44, v44, 0x3dd53b94, v56
	v_fmamk_f32 v45, v45, 0x3dd53b94, v56
	v_fmamk_f32 v46, v46, 0x3dd53b94, v56
	v_exp_f32_e32 v156, v36
	v_exp_f32_e32 v158, v37
	v_exp_f32_e32 v154, v38
	v_exp_f32_e32 v155, v39
	v_exp_f32_e32 v151, v40
	v_exp_f32_e32 v153, v41
	v_exp_f32_e32 v150, v42
	v_exp_f32_e32 v152, v43
	v_exp_f32_e32 v147, v44
	v_exp_f32_e32 v149, v45
	v_exp_f32_e32 v146, v46
	v_exp_f32_e32 v148, v57
	s_waitcnt vmcnt(0)
	s_addk_i32 s6, 0x4000
	s_waitcnt vmcnt(4)
	ds_write_b128 v185, v[16:19] offset:16384
	s_waitcnt vmcnt(2)
	ds_write_b128 v186, v[20:23] offset:16384
	s_waitcnt vmcnt(1)
	ds_write_b128 v187, v[24:27] offset:49152
	s_waitcnt vmcnt(0)
	ds_write_b128 v188, v[28:31] offset:49152
	ds_write_b128 v209, v[32:35]
	v_add_u32_e32 v184, s6, v54
	v_mov_b64_e32 v[62:63], v[14:15]
	v_mov_b64_e32 v[46:47], v[14:15]
	v_mov_b64_e32 v[30:31], v[14:15]
	v_cmp_gt_u32_e64 s[4:5], 32, v174
	s_addk_i32 s46, 0x4080
	s_addk_i32 s68, 0xff80
	v_mov_b64_e32 v[60:61], v[12:13]
	v_mov_b64_e32 v[58:59], v[10:11]
	v_mov_b64_e32 v[56:57], v[8:9]
	v_mov_b64_e32 v[54:55], v[6:7]
	v_mov_b64_e32 v[52:53], v[4:5]
	v_mov_b64_e32 v[50:51], v[2:3]
	v_mov_b64_e32 v[48:49], v[0:1]
	v_mov_b64_e32 v[44:45], v[12:13]
	v_mov_b64_e32 v[42:43], v[10:11]
	v_mov_b64_e32 v[40:41], v[8:9]
	v_mov_b64_e32 v[38:39], v[6:7]
	v_mov_b64_e32 v[36:37], v[4:5]
	v_mov_b64_e32 v[34:35], v[2:3]
	v_mov_b64_e32 v[32:33], v[0:1]
	v_mov_b64_e32 v[28:29], v[12:13]
	v_mov_b64_e32 v[26:27], v[10:11]
	v_mov_b64_e32 v[24:25], v[8:9]
	v_mov_b64_e32 v[22:23], v[6:7]
	v_mov_b64_e32 v[20:21], v[4:5]
	v_mov_b64_e32 v[18:19], v[2:3]
	v_mov_b64_e32 v[16:17], v[0:1]
	v_mul_lo_u32 v232, v163, s40
	v_mul_lo_u32 v233, v162, s41
	v_mad_u64_u32 v[234:235], s[100:101], v162, s40, 0
	v_add3_u32 v235, v235, v233, v232
	v_lshlrev_b64 v[234:235], 1, v[234:235]
	v_mul_lo_u32 v232, v167, s40
	v_mul_lo_u32 v233, v166, s41
	v_mad_u64_u32 v[236:237], s[100:101], v166, s40, 0
	v_add3_u32 v237, v237, v233, v232
	v_lshlrev_b64 v[236:237], 1, v[236:237]
	v_lshl_add_u64 v[162:163], v[168:169], 0, v[234:235]
	v_lshl_add_u64 v[166:167], v[168:169], 0, v[236:237]
	v_lshl_add_u64 v[168:169], v[170:171], 0, v[234:235]
	v_lshl_add_u64 v[170:171], v[170:171], 0, v[236:237]
	s_waitcnt lgkmcnt(0)
.Lmla_head:
	s_barrier
.LBB0_762:
	ds_read_b128 v[64:67], v189 offset:49152
	ds_read_b128 v[68:71], v189 offset:57344
	ds_read_b128 v[236:239], v191 offset:49152
	ds_read_b128 v[240:243], v191 offset:57344
	ds_read_b128 v[244:247], v193 offset:49152
	ds_read_b128 v[248:251], v193 offset:57344
	s_add_i32 s9, s24, -1
	s_cmp_lt_u32 s9, 3
	s_cselect_b32 s100, s46, s68
	s_add_i32 s100, s100, s8
	s_ashr_i32 s101, s100, 31
	s_mul_hi_u32 s7, s100, s40
	s_mul_i32 s6, s100, s41
	s_add_u32 s7, s7, s6
	s_mul_i32 s6, s101, s40
	s_add_u32 s7, s7, s6
	s_mul_i32 s6, s100, s40
	s_lshl_b64 s[6:7], s[6:7], 1
	s_add_i32 s0, 0, 0x12800
	s_waitcnt lgkmcnt(5)
	v_mfma_f32_32x32x16_bf16 v[80:95], v[64:67], v[124:127], 0
	v_exp_f32_e32 v140, v140
	v_exp_f32_e32 v141, v141
	v_add_u32_e32 v211, s0, v198
	s_waitcnt lgkmcnt(4)
	v_mfma_f32_32x32x16_bf16 v[64:79], v[68:71], v[124:127], 0
	v_exp_f32_e32 v138, v138
	v_exp_f32_e32 v139, v139
	v_add_u32_e32 v210, s0, v200
	s_waitcnt lgkmcnt(3)
	v_mfma_f32_32x32x16_bf16 v[80:95], v[236:239], v[120:123], v[80:95]
	ds_read_b128 v[236:239], v195 offset:49152
	v_exp_f32_e32 v214, v130
	v_exp_f32_e32 v215, v131
	v_add_u32_e32 v216, s0, v202
	s_waitcnt lgkmcnt(3)
	v_mfma_f32_32x32x16_bf16 v[64:79], v[240:243], v[120:123], v[64:79]
	ds_read_b128 v[240:243], v195 offset:57344
	v_exp_f32_e32 v142, v142
	v_exp_f32_e32 v143, v143
	v_add_u32_e32 v217, s0, v204
	s_waitcnt lgkmcnt(3)
	v_mfma_f32_32x32x16_bf16 v[80:95], v[244:247], v[116:119], v[80:95]
	ds_read_b128 v[244:247], v196 offset:49152
	v_exp_f32_e32 v136, v136
	v_exp_f32_e32 v137, v137
	v_cvt_pk_bf16_f32 v130, v156, v158
	s_waitcnt lgkmcnt(3)
	v_mfma_f32_32x32x16_bf16 v[64:79], v[248:251], v[116:119], v[64:79]
	ds_read_b128 v[248:251], v196 offset:57344
	v_exp_f32_e32 v212, v132
	v_exp_f32_e32 v213, v133
	v_cvt_pk_bf16_f32 v131, v154, v155
	s_waitcnt lgkmcnt(3)
	v_mfma_f32_32x32x16_bf16 v[80:95], v[236:239], v[112:115], v[80:95]
	ds_read_b128 v[236:239], v194 offset:49152
	v_exp_f32_e32 v220, v128
	v_add_f32_e32 v128, 0, v159
	v_add_f32_e32 v128, v161, v128
	v_add_f32_e32 v128, v157, v128
	s_waitcnt lgkmcnt(3)
	v_mfma_f32_32x32x16_bf16 v[64:79], v[240:243], v[112:115], v[64:79]
	ds_read_b128 v[240:243], v194 offset:57344
	v_add_f32_e32 v128, v160, v128
	v_add_f32_e32 v128, v156, v128
	v_add_f32_e32 v128, v158, v128
	v_add_f32_e32 v128, v154, v128
	v_add_f32_e32 v128, v155, v128
	s_waitcnt lgkmcnt(3)
	v_mfma_f32_32x32x16_bf16 v[80:95], v[244:247], v[108:111], v[80:95]
	ds_read_b128 v[244:247], v192 offset:49152
	v_add_f32_e32 v128, v151, v128
	v_add_f32_e32 v128, v153, v128
	v_add_f32_e32 v128, v150, v128
	v_add_f32_e32 v128, v152, v128
	v_add_f32_e32 v128, v147, v128
	s_waitcnt lgkmcnt(3)
	v_mfma_f32_32x32x16_bf16 v[64:79], v[248:251], v[108:111], v[64:79]
	ds_read_b128 v[248:251], v192 offset:57344
	v_add_f32_e32 v128, v149, v128
	v_add_f32_e32 v128, v146, v128
	v_add_f32_e32 v128, v148, v128
	v_add_f32_e32 v128, v140, v128
	v_add_f32_e32 v128, v141, v128
	s_waitcnt lgkmcnt(3)
	v_mfma_f32_32x32x16_bf16 v[80:95], v[236:239], v[104:107], v[80:95]
	ds_read_b128 v[236:239], v190 offset:49152
	v_add_f32_e32 v128, v138, v128
	v_add_f32_e32 v128, v139, v128
	v_add_f32_e32 v128, v212, v128
	v_exp_f32_e32 v221, v129
	s_waitcnt lgkmcnt(3)
	v_mfma_f32_32x32x16_bf16 v[64:79], v[240:243], v[104:107], v[64:79]
	ds_read_b128 v[240:243], v190 offset:57344
	v_add_f32_e32 v128, v213, v128
	v_add_f32_e32 v128, v214, v128
	v_add_f32_e32 v128, v215, v128
	v_add_f32_e32 v128, v220, v128
	v_add_f32_e32 v128, v221, v128
	s_waitcnt lgkmcnt(3)
	v_mfma_f32_32x32x16_bf16 v[80:95], v[244:247], v[100:103], v[80:95]
	ds_read_b128 v[244:247], v211
	v_exp_f32_e32 v223, v134
	v_add_f32_e32 v128, v142, v128
	v_exp_f32_e32 v224, v135
	s_waitcnt lgkmcnt(3)
	v_mfma_f32_32x32x16_bf16 v[64:79], v[248:251], v[100:103], v[64:79]
	v_add_f32_e32 v128, v143, v128
	v_add_f32_e32 v128, v136, v128
	v_add_f32_e32 v128, v137, v128
	v_add_f32_e32 v128, v223, v128
	v_add_f32_e32 v218, v224, v128
	s_waitcnt lgkmcnt(2)
	v_mfma_f32_32x32x16_bf16 v[80:95], v[236:239], v[96:99], v[80:95]
	ds_read_b128 v[236:239], v211 offset:4096
	ds_read_b128 v[248:251], v182
	v_mov_b32_e32 v219, v218
	v_cvt_pk_bf16_f32 v128, v159, v161
	v_cvt_pk_bf16_f32 v129, v157, v160
	v_cvt_pk_bf16_f32 v132, v151, v153
	v_cvt_pk_bf16_f32 v133, v150, v152
	s_waitcnt lgkmcnt(3)
	v_mfma_f32_32x32x16_bf16 v[64:79], v[240:243], v[96:99], v[64:79]
	ds_read_b128 v[240:243], v210
	v_cvt_pk_bf16_f32 v134, v147, v149
	v_cvt_pk_bf16_f32 v135, v146, v148
	v_cvt_pk_bf16_f32 v154, v140, v141
	v_cvt_pk_bf16_f32 v155, v138, v139
	v_cvt_pk_bf16_f32 v156, v212, v213
	s_waitcnt lgkmcnt(1)
	v_mfma_f32_32x32x16_bf16 v[80:95], v[244:247], v[248:251], v[80:95]
	v_cvt_pk_bf16_f32 v157, v214, v215
	v_cvt_pk_bf16_f32 v220, v220, v221
	v_cvt_pk_bf16_f32 v221, v142, v143
	v_cvt_pk_bf16_f32 v222, v136, v137
	v_permlane32_swap_b32_e32 v218, v219
	v_mfma_f32_32x32x16_bf16 v[64:79], v[236:239], v[248:251], v[64:79]
	ds_read_b128 v[248:251], v210 offset:4096
	ds_read_b128 v[244:247], v182 offset:1024
	ds_read_b128 v[236:239], v216
	v_permlane32_swap_b32_e32 v128, v130
	v_cvt_pk_bf16_f32 v223, v223, v224
	v_permlane32_swap_b32_e32 v220, v222
	v_permlane32_swap_b32_e32 v129, v131
	v_permlane32_swap_b32_e32 v132, v134
	s_waitcnt lgkmcnt(1)
	v_mfma_f32_32x32x16_bf16 v[80:95], v[240:243], v[244:247], v[80:95]
	v_permlane32_swap_b32_e32 v133, v135
	v_permlane32_swap_b32_e32 v154, v156
	v_permlane32_swap_b32_e32 v155, v157
	v_permlane32_swap_b32_e32 v221, v223
	v_lshl_add_u64 v[136:137], s[6:7], 0, v[162:163]
	v_mfma_f32_32x32x16_bf16 v[64:79], v[248:251], v[244:247], v[64:79]
	ds_read_b128 v[244:247], v216 offset:4096
	ds_read_b128 v[240:243], v182 offset:2048
	ds_read_b128 v[248:251], v217
	v_lshl_add_u64 v[140:141], s[6:7], 0, v[166:167]
	v_lshl_add_u64 v[146:147], s[6:7], 0, v[168:169]
	v_lshl_add_u64 v[150:151], s[6:7], 0, v[170:171]
	v_lshl_add_u64 v[158:159], s[100:101], 0, v[164:165]
	v_mad_u64_u32 v[160:161], s[100:101], v158, s3, v[172:173]
	s_waitcnt lgkmcnt(1)
	v_mfma_f32_32x32x16_bf16 v[80:95], v[236:239], v[240:243], v[80:95]
	v_mad_i32_i24 v161, v159, s3, v161
	v_mfma_f32_32x32x16_bf16 v[64:79], v[244:247], v[240:243], v[64:79]
	ds_read_b128 v[240:243], v217 offset:4096
	ds_read_b128 v[236:239], v182 offset:3072
	ds_read_b64_tr_b16 v[224:225], v181 offset:0
	ds_read_b64_tr_b16 v[226:227], v181 offset:0x800
	ds_read_b64_tr_b16 v[232:233], v181 offset:0x1000
	ds_read_b64_tr_b16 v[234:235], v181 offset:0x1800
	s_waitcnt lgkmcnt(4)
	v_mfma_f32_32x32x16_bf16 v[80:95], v[248:251], v[236:239], v[80:95]
	v_mfma_f32_32x32x16_bf16 v[64:79], v[240:243], v[236:239], v[64:79]
	ds_read_b64_tr_b16 v[236:237], v181 offset:0x2000
	ds_read_b64_tr_b16 v[238:239], v181 offset:0x2800
	ds_read_b64_tr_b16 v[240:241], v181 offset:0x3000
	ds_read_b64_tr_b16 v[242:243], v181 offset:0x3800
	ds_read_b64_tr_b16 v[212:213], v181 offset:0x200
	ds_read_b64_tr_b16 v[214:215], v181 offset:0xa00
	global_load_dwordx4 v[136:139], v[136:137], off
	global_load_dwordx4 v[140:143], v[140:141], off
	global_load_dwordx4 v[146:149], v[146:147], off
	global_load_dwordx4 v[150:153], v[150:151], off
	global_load_dwordx4 v[158:161], v[160:161], off
	s_waitcnt lgkmcnt(8)
	v_mfma_f32_32x32x16_bf16 v[0:15], v[128:131], v[224:227], v[0:15]
	ds_read_b64_tr_b16 v[224:225], v181 offset:0x1200
	ds_read_b64_tr_b16 v[226:227], v181 offset:0x1a00
	v_max_f32_e32 v250, v81, v81
	v_max_f32_e32 v251, v80, v80
	v_max_f32_e32 v250, v251, v250
	v_max3_f32 v250, v250, v82, v83
	v_max3_f32 v250, v250, v84, v85
	s_waitcnt lgkmcnt(8)
	v_mfma_f32_32x32x16_bf16 v[0:15], v[132:135], v[232:235], v[0:15]
	ds_read_b64_tr_b16 v[232:233], v181 offset:0x2200
	ds_read_b64_tr_b16 v[234:235], v181 offset:0x2a00
	v_max3_f32 v250, v250, v86, v87
	v_max3_f32 v250, v250, v88, v89
	v_max3_f32 v250, v250, v90, v91
	v_max3_f32 v250, v250, v92, v93
	v_max3_f32 v250, v250, v94, v95
	s_waitcnt lgkmcnt(8)
	v_mfma_f32_32x32x16_bf16 v[0:15], v[154:157], v[236:239], v[0:15]
	ds_read_b64_tr_b16 v[236:237], v181 offset:0x3200
	ds_read_b64_tr_b16 v[238:239], v181 offset:0x3a00
	v_max3_f32 v250, v250, v64, v65
	v_max3_f32 v250, v250, v66, v67
	v_max3_f32 v250, v250, v68, v69
	v_max3_f32 v250, v250, v70, v71
	v_max3_f32 v250, v250, v72, v73
	s_waitcnt lgkmcnt(8)
	v_mfma_f32_32x32x16_bf16 v[0:15], v[220:223], v[240:243], v[0:15]
	ds_read_b64_tr_b16 v[240:241], v181 offset:0x400
	ds_read_b64_tr_b16 v[242:243], v181 offset:0xc00
	v_max3_f32 v250, v250, v74, v75
	v_max3_f32 v250, v250, v76, v77
	v_max3_f32 v250, v250, v78, v79
	v_mov_b32_e32 v251, v250
	s_nop 1
	v_permlane32_swap_b32_e32 v250, v251
	s_waitcnt lgkmcnt(8)
	v_mfma_f32_32x32x16_bf16 v[48:63], v[128:131], v[212:215], v[48:63]
	ds_read_b64_tr_b16 v[212:213], v181 offset:0x1400
	ds_read_b64_tr_b16 v[214:215], v181 offset:0x1c00
	v_max_f32_e32 v251, v251, v251
	v_max_f32_e32 v250, v250, v250
	v_max_f32_e32 v250, v250, v251
	v_sub_f32_e32 v251, v250, v207
	v_cmp_ge_f32_e32 vcc, s94, v251
	s_waitcnt lgkmcnt(8)
	v_mfma_f32_32x32x16_bf16 v[48:63], v[132:135], v[224:227], v[48:63]
	ds_read_b64_tr_b16 v[224:225], v181 offset:0x2400
	ds_read_b64_tr_b16 v[226:227], v181 offset:0x2c00
	v_max_f32_e32 v251, v207, v207
	v_max_f32_e32 v250, v251, v250
	v_sub_f32_e32 v251, v207, v250
	v_mul_f32_e32 v251, 0x3dd53b94, v251
	s_waitcnt lgkmcnt(8)
	v_mfma_f32_32x32x16_bf16 v[48:63], v[154:157], v[232:235], v[48:63]
	ds_read_b64_tr_b16 v[232:233], v181 offset:0x3400
	ds_read_b64_tr_b16 v[234:235], v181 offset:0x3c00
	v_exp_f32_e32 v251, v251
	s_waitcnt lgkmcnt(8)
	v_mfma_f32_32x32x16_bf16 v[48:63], v[220:223], v[236:239], v[48:63]
	ds_read_b64_tr_b16 v[236:237], v181 offset:0x600
	ds_read_b64_tr_b16 v[238:239], v181 offset:0xe00
	s_waitcnt lgkmcnt(8)
	v_mfma_f32_32x32x16_bf16 v[32:47], v[128:131], v[240:243], v[32:47]
	ds_read_b64_tr_b16 v[240:241], v181 offset:0x1600
	ds_read_b64_tr_b16 v[242:243], v181 offset:0x1e00
	s_waitcnt lgkmcnt(8)
	v_mfma_f32_32x32x16_bf16 v[32:47], v[132:135], v[212:215], v[32:47]
	ds_read_b64_tr_b16 v[212:213], v181 offset:0x2600
	ds_read_b64_tr_b16 v[214:215], v181 offset:0x2e00
	s_waitcnt lgkmcnt(8)
	v_mfma_f32_32x32x16_bf16 v[32:47], v[154:157], v[224:227], v[32:47]
	ds_read_b64_tr_b16 v[224:225], v181 offset:0x3600
	ds_read_b64_tr_b16 v[226:227], v181 offset:0x3e00
	s_waitcnt lgkmcnt(8)
	v_mfma_f32_32x32x16_bf16 v[32:47], v[220:223], v[232:235], v[32:47]
	s_waitcnt lgkmcnt(6)
	v_mfma_f32_32x32x16_bf16 v[16:31], v[128:131], v[236:239], v[16:31]
	s_waitcnt lgkmcnt(4)
	v_mfma_f32_32x32x16_bf16 v[16:31], v[132:135], v[240:243], v[16:31]
	s_waitcnt lgkmcnt(2)
	v_mfma_f32_32x32x16_bf16 v[16:31], v[154:157], v[212:215], v[16:31]
	s_waitcnt lgkmcnt(0)
	v_mfma_f32_32x32x16_bf16 v[16:31], v[220:223], v[224:227], v[16:31]
	s_cmp_eq_u64 vcc, exec
	s_cselect_b64 s[6:7], -1, 0
	s_barrier
	s_waitcnt vmcnt(0)
	v_cndmask_b32_e64 v220, v251, 1.0, s[6:7]
	v_add_u32_e32 v129, 0x10800, v208
	ds_write_b128 v187, v[146:149] offset:32768
	ds_write_b128 v188, v[150:153] offset:32768
	ds_write_b128 v129, v[158:161]
	ds_write_b128 v185, v[136:139]
	ds_write_b128 v186, v[140:143]
	s_nop 0
	s_nop 0
	s_nop 0
	s_nop 0
	s_nop 0
	s_and_b64 vcc, exec, s[6:7]
	s_cbranch_vccz .Lresc_766

.LBB0_770:
	v_cndmask_b32_e64 v207, v250, v207, s[6:7]
	v_mul_f32_e32 v134, 0xbdd53b94, v207
	v_mov_b32_e32 v135, v134
	v_fmamk_f32 v80, v80, 0x3dd53b94, v134
	v_fmamk_f32 v81, v81, 0x3dd53b94, v134
	v_fmamk_f32 v82, v82, 0x3dd53b94, v134
	v_fmamk_f32 v83, v83, 0x3dd53b94, v134
	v_fmamk_f32 v84, v84, 0x3dd53b94, v134
	v_fmamk_f32 v85, v85, 0x3dd53b94, v134
	v_fmamk_f32 v86, v86, 0x3dd53b94, v134
	v_fmamk_f32 v87, v87, 0x3dd53b94, v134
	v_fmamk_f32 v88, v88, 0x3dd53b94, v134
	v_fmamk_f32 v89, v89, 0x3dd53b94, v134
	v_fmamk_f32 v90, v90, 0x3dd53b94, v134
	v_fmamk_f32 v91, v91, 0x3dd53b94, v134
	v_fmamk_f32 v92, v92, 0x3dd53b94, v134
	v_fmamk_f32 v93, v93, 0x3dd53b94, v134
	v_fmamk_f32 v94, v94, 0x3dd53b94, v134
	v_fmac_f32_e32 v135, 0x3dd53b94, v95
	v_exp_f32_e32 v159, v80
	v_exp_f32_e32 v161, v81
	v_exp_f32_e32 v157, v82
	v_exp_f32_e32 v160, v83
	v_exp_f32_e32 v156, v84
	v_exp_f32_e32 v158, v85
	v_exp_f32_e32 v154, v86
	v_exp_f32_e32 v155, v87
	v_exp_f32_e32 v151, v88
	v_exp_f32_e32 v153, v89
	v_exp_f32_e32 v150, v90
	v_exp_f32_e32 v152, v91
	v_exp_f32_e32 v147, v92
	v_exp_f32_e32 v149, v93
	v_exp_f32_e32 v146, v94
	v_exp_f32_e32 v148, v135
	v_fma_f32 v140, v64, s76, v134
	v_fma_f32 v141, v65, s76, v134
	v_add_f32_e32 v64, v218, v219
	v_fmac_f32_e32 v64, v206, v197
	v_add_f32_e32 v197, v222, v223
	s_addk_i32 s8, 0x80
	s_add_i32 s24, s24, 2
	v_fma_f32 v138, v66, s76, v134
	v_fma_f32 v139, v67, s76, v134
	v_fma_f32 v132, v68, s76, v134
	v_fma_f32 v133, v69, s76, v134
	v_fma_f32 v130, v70, s76, v134
	v_fma_f32 v131, v71, s76, v134
	v_fma_f32 v128, v72, s76, v134
	v_fma_f32 v129, v73, s76, v134
	v_fma_f32 v142, v74, s76, v134
	v_fma_f32 v143, v75, s76, v134
	v_fma_f32 v136, v76, s76, v134
	v_fma_f32 v137, v77, s76, v134
	v_fma_f32 v135, v79, s76, v134
	v_fma_f32 v134, v78, s76, v134
	v_fmac_f32_e32 v197, v64, v220
	s_cmp_ge_u32 s24, s91
	s_waitcnt lgkmcnt(2)
	s_cbranch_scc1 .Lmla_exitbar
	v_mov_b32_e32 v206, v221
	s_branch .Lmla_head

.Lresc_766:
	s_and_saveexec_b64 s[0:1], s[4:5]
	ds_write_b32 v183, v220 offset:128
	s_or_b64 exec, exec, s[0:1]
	s_waitcnt lgkmcnt(0)
	v_add_u32_e32 v129, v180, v144
	ds_read_b128 v[130:133], v129 offset:224
	ds_read_b128 v[134:137], v129 offset:192
	ds_read_b128 v[138:141], v129 offset:160
	ds_read_b128 v[146:149], v129 offset:128
	s_waitcnt lgkmcnt(3)
	v_pk_mul_f32 v[12:13], v[12:13], v[130:131]
	s_waitcnt lgkmcnt(2)
	v_pk_mul_f32 v[8:9], v[8:9], v[134:135]
	s_waitcnt lgkmcnt(1)
	v_pk_mul_f32 v[4:5], v[4:5], v[138:139]
	v_pk_mul_f32 v[14:15], v[14:15], v[132:133]
	v_pk_mul_f32 v[10:11], v[10:11], v[136:137]
	v_pk_mul_f32 v[6:7], v[6:7], v[140:141]
	s_waitcnt lgkmcnt(0)
	v_pk_mul_f32 v[2:3], v[2:3], v[148:149]
	v_pk_mul_f32 v[0:1], v[0:1], v[146:147]
	v_pk_mul_f32 v[60:61], v[60:61], v[130:131]
	v_pk_mul_f32 v[56:57], v[56:57], v[134:135]
	v_pk_mul_f32 v[52:53], v[52:53], v[138:139]
	v_pk_mul_f32 v[62:63], v[62:63], v[132:133]
	v_pk_mul_f32 v[58:59], v[58:59], v[136:137]
	v_pk_mul_f32 v[54:55], v[54:55], v[140:141]
	v_pk_mul_f32 v[50:51], v[50:51], v[148:149]
	v_pk_mul_f32 v[48:49], v[48:49], v[146:147]
	v_pk_mul_f32 v[44:45], v[44:45], v[130:131]
	v_pk_mul_f32 v[40:41], v[40:41], v[134:135]
	v_pk_mul_f32 v[36:37], v[36:37], v[138:139]
	v_pk_mul_f32 v[46:47], v[46:47], v[132:133]
	v_pk_mul_f32 v[42:43], v[42:43], v[136:137]
	v_pk_mul_f32 v[38:39], v[38:39], v[140:141]
	v_pk_mul_f32 v[34:35], v[34:35], v[148:149]
	v_pk_mul_f32 v[32:33], v[32:33], v[146:147]
	v_pk_mul_f32 v[28:29], v[28:29], v[130:131]
	v_pk_mul_f32 v[24:25], v[24:25], v[134:135]
	v_pk_mul_f32 v[20:21], v[20:21], v[138:139]
	v_pk_mul_f32 v[30:31], v[30:31], v[132:133]
	v_pk_mul_f32 v[26:27], v[26:27], v[136:137]
	v_pk_mul_f32 v[22:23], v[22:23], v[140:141]
	v_pk_mul_f32 v[18:19], v[18:19], v[148:149]
	v_pk_mul_f32 v[16:17], v[16:17], v[146:147]
	s_branch .LBB0_766
.Lmla_exitbar:
	s_barrier
.LBB0_772:
	ds_read_b128 v[64:67], v189 offset:49152
	ds_read_b128 v[68:71], v189 offset:57344
	s_waitcnt lgkmcnt(1)
	v_mfma_f32_32x32x16_bf16 v[80:95], v[64:67], v[124:127], 0
	s_waitcnt lgkmcnt(0)
	v_mfma_f32_32x32x16_bf16 v[64:79], v[68:71], v[124:127], 0
	ds_read_b128 v[124:127], v191 offset:49152
	ds_read_b128 v[162:165], v191 offset:57344
	s_waitcnt lgkmcnt(1)
	v_mfma_f32_32x32x16_bf16 v[80:95], v[124:127], v[120:123], v[80:95]
	s_waitcnt lgkmcnt(0)
	v_mfma_f32_32x32x16_bf16 v[64:79], v[162:165], v[120:123], v[64:79]
	ds_read_b128 v[120:123], v193 offset:49152
	ds_read_b128 v[124:127], v193 offset:57344
	s_waitcnt lgkmcnt(1)
	v_mfma_f32_32x32x16_bf16 v[80:95], v[120:123], v[116:119], v[80:95]
	s_waitcnt lgkmcnt(0)
	v_mfma_f32_32x32x16_bf16 v[64:79], v[124:127], v[116:119], v[64:79]
	ds_read_b128 v[116:119], v195 offset:49152
	ds_read_b128 v[120:123], v195 offset:57344
	s_waitcnt lgkmcnt(1)
	v_mfma_f32_32x32x16_bf16 v[80:95], v[116:119], v[112:115], v[80:95]
	s_waitcnt lgkmcnt(0)
	v_mfma_f32_32x32x16_bf16 v[64:79], v[120:123], v[112:115], v[64:79]
	ds_read_b128 v[112:115], v196 offset:49152
	ds_read_b128 v[116:119], v196 offset:57344
	v_exp_f32_e32 v120, v134
	v_exp_f32_e32 v121, v135
	s_waitcnt lgkmcnt(1)
	v_mfma_f32_32x32x16_bf16 v[80:95], v[112:115], v[108:111], v[80:95]
	s_waitcnt lgkmcnt(0)
	v_mfma_f32_32x32x16_bf16 v[64:79], v[116:119], v[108:111], v[64:79]
	ds_read_b128 v[108:111], v194 offset:49152
	ds_read_b128 v[112:115], v194 offset:57344
	v_exp_f32_e32 v116, v142
	v_exp_f32_e32 v117, v143
	v_exp_f32_e32 v118, v136
	v_exp_f32_e32 v119, v137
	s_waitcnt lgkmcnt(1)
	v_mfma_f32_32x32x16_bf16 v[80:95], v[108:111], v[104:107], v[80:95]
	s_waitcnt lgkmcnt(0)
	v_mfma_f32_32x32x16_bf16 v[64:79], v[112:115], v[104:107], v[64:79]
	ds_read_b128 v[104:107], v192 offset:49152
	ds_read_b128 v[108:111], v192 offset:57344
	v_exp_f32_e32 v112, v130
	v_exp_f32_e32 v113, v131
	v_exp_f32_e32 v114, v128
	v_exp_f32_e32 v115, v129
	s_waitcnt lgkmcnt(1)
	v_mfma_f32_32x32x16_bf16 v[80:95], v[104:107], v[100:103], v[80:95]
	s_waitcnt lgkmcnt(0)
	v_mfma_f32_32x32x16_bf16 v[64:79], v[108:111], v[100:103], v[64:79]
	ds_read_b128 v[100:103], v190 offset:49152
	ds_read_b128 v[104:107], v190 offset:57344
	v_exp_f32_e32 v108, v138
	v_exp_f32_e32 v109, v139
	v_exp_f32_e32 v110, v132
	v_exp_f32_e32 v111, v133
	s_waitcnt lgkmcnt(1)
	v_mfma_f32_32x32x16_bf16 v[80:95], v[100:103], v[96:99], v[80:95]
	s_waitcnt lgkmcnt(0)
	v_mfma_f32_32x32x16_bf16 v[64:79], v[104:107], v[96:99], v[64:79]
	ds_read_b128 v[96:99], v211
	ds_read_b128 v[100:103], v211 offset:4096
	ds_read_b128 v[104:107], v182
	s_waitcnt lgkmcnt(0)
	v_mfma_f32_32x32x16_bf16 v[80:95], v[96:99], v[104:107], v[80:95]
	v_mfma_f32_32x32x16_bf16 v[64:79], v[100:103], v[104:107], v[64:79]
	ds_read_b128 v[96:99], v210
	ds_read_b128 v[100:103], v210 offset:4096
	ds_read_b128 v[104:107], v182 offset:1024
	s_waitcnt lgkmcnt(0)
	v_mfma_f32_32x32x16_bf16 v[80:95], v[96:99], v[104:107], v[80:95]
	v_mfma_f32_32x32x16_bf16 v[64:79], v[100:103], v[104:107], v[64:79]
	ds_read_b128 v[96:99], v216
	ds_read_b128 v[100:103], v216 offset:4096
	ds_read_b128 v[104:107], v182 offset:2048
	s_waitcnt lgkmcnt(0)
	v_mfma_f32_32x32x16_bf16 v[80:95], v[96:99], v[104:107], v[80:95]
	v_mfma_f32_32x32x16_bf16 v[64:79], v[100:103], v[104:107], v[64:79]
	ds_read_b128 v[96:99], v217
	ds_read_b128 v[100:103], v217 offset:4096
	ds_read_b128 v[104:107], v182 offset:3072
	s_waitcnt lgkmcnt(0)
	v_mfma_f32_32x32x16_bf16 v[80:95], v[96:99], v[104:107], v[80:95]
	v_add_f32_e32 v96, 0, v159
	v_add_f32_e32 v96, v161, v96
	v_add_f32_e32 v96, v157, v96
	v_add_f32_e32 v96, v160, v96
	v_add_f32_e32 v96, v156, v96
	v_add_f32_e32 v96, v158, v96
	v_add_f32_e32 v96, v154, v96
	v_add_f32_e32 v96, v155, v96
	v_add_f32_e32 v96, v151, v96
	v_add_f32_e32 v96, v153, v96
	v_add_f32_e32 v96, v150, v96
	v_add_f32_e32 v96, v152, v96
	v_mfma_f32_32x32x16_bf16 v[64:79], v[100:103], v[104:107], v[64:79]
	v_exp_f32_e32 v106, v140
	v_add_f32_e32 v96, v147, v96
	v_exp_f32_e32 v107, v141
	v_add_f32_e32 v96, v149, v96
	v_add_f32_e32 v96, v146, v96
	v_add_f32_e32 v96, v148, v96
	v_add_f32_e32 v96, v106, v96
	v_add_f32_e32 v96, v107, v96
	v_add_f32_e32 v96, v108, v96
	v_add_f32_e32 v96, v109, v96
	v_add_f32_e32 v96, v110, v96
	v_add_f32_e32 v96, v111, v96
	v_add_f32_e32 v96, v112, v96
	v_add_f32_e32 v96, v113, v96
	v_add_f32_e32 v96, v114, v96
	v_add_f32_e32 v96, v115, v96
	v_add_f32_e32 v96, v116, v96
	v_add_f32_e32 v96, v117, v96
	v_add_f32_e32 v96, v118, v96
	v_add_f32_e32 v96, v119, v96
	v_add_f32_e32 v96, v120, v96
	v_add_f32_e32 v100, v121, v96
	v_mov_b32_e32 v101, v100
	v_cvt_pk_bf16_f32 v96, v159, v161
	v_cvt_pk_bf16_f32 v97, v157, v160
	v_cvt_pk_bf16_f32 v98, v156, v158
	v_cvt_pk_bf16_f32 v99, v154, v155
	s_nop 1
	v_permlane32_swap_b32_e32 v100, v101
	v_permlane32_swap_b32_e32 v96, v98
	v_permlane32_swap_b32_e32 v97, v99
	v_cvt_pk_bf16_f32 v102, v151, v153
	v_cvt_pk_bf16_f32 v103, v150, v152
	v_cvt_pk_bf16_f32 v104, v147, v149
	v_cvt_pk_bf16_f32 v105, v146, v148
	v_cvt_pk_bf16_f32 v106, v106, v107
	v_cvt_pk_bf16_f32 v107, v108, v109
	v_cvt_pk_bf16_f32 v108, v110, v111
	v_cvt_pk_bf16_f32 v109, v112, v113
	v_cvt_pk_bf16_f32 v110, v114, v115
	v_cvt_pk_bf16_f32 v111, v116, v117
	v_cvt_pk_bf16_f32 v112, v118, v119
	v_cvt_pk_bf16_f32 v113, v120, v121
	s_nop 0
	v_permlane32_swap_b32_e32 v102, v104
	v_permlane32_swap_b32_e32 v103, v105
	v_permlane32_swap_b32_e32 v106, v108
	v_permlane32_swap_b32_e32 v107, v109
	v_permlane32_swap_b32_e32 v110, v112
	v_permlane32_swap_b32_e32 v111, v113
	ds_read_b64_tr_b16 v[114:115], v181 offset:0
	ds_read_b64_tr_b16 v[116:117], v181 offset:0x800
	ds_read_b64_tr_b16 v[118:119], v181 offset:0x1000
	ds_read_b64_tr_b16 v[120:121], v181 offset:0x1800
	ds_read_b64_tr_b16 v[122:123], v181 offset:0x2000
	ds_read_b64_tr_b16 v[124:125], v181 offset:0x2800
	ds_read_b64_tr_b16 v[126:127], v181 offset:0x3000
	ds_read_b64_tr_b16 v[128:129], v181 offset:0x3800
	s_waitcnt lgkmcnt(0)
	s_nop 0
	v_mfma_f32_32x32x16_bf16 v[0:15], v[96:99], v[114:117], v[0:15]
	ds_read_b64_tr_b16 v[114:115], v181 offset:0x200
	ds_read_b64_tr_b16 v[116:117], v181 offset:0xa00
	v_mfma_f32_32x32x16_bf16 v[0:15], v[102:105], v[118:121], v[0:15]
	ds_read_b64_tr_b16 v[118:119], v181 offset:0x1200
	ds_read_b64_tr_b16 v[120:121], v181 offset:0x1a00
	v_mfma_f32_32x32x16_bf16 v[0:15], v[106:109], v[122:125], v[0:15]
	ds_read_b64_tr_b16 v[122:123], v181 offset:0x2200
	ds_read_b64_tr_b16 v[124:125], v181 offset:0x2a00
	v_mfma_f32_32x32x16_bf16 v[0:15], v[110:113], v[126:129], v[0:15]
	ds_read_b64_tr_b16 v[126:127], v181 offset:0x3200
	ds_read_b64_tr_b16 v[128:129], v181 offset:0x3a00
	s_waitcnt lgkmcnt(0)
	v_mfma_f32_32x32x16_bf16 v[48:63], v[96:99], v[114:117], v[48:63]
	ds_read_b64_tr_b16 v[114:115], v181 offset:0x400
	ds_read_b64_tr_b16 v[116:117], v181 offset:0xc00
	v_mfma_f32_32x32x16_bf16 v[48:63], v[102:105], v[118:121], v[48:63]
	ds_read_b64_tr_b16 v[118:119], v181 offset:0x1400
	ds_read_b64_tr_b16 v[120:121], v181 offset:0x1c00
	v_mfma_f32_32x32x16_bf16 v[48:63], v[106:109], v[122:125], v[48:63]
	ds_read_b64_tr_b16 v[122:123], v181 offset:0x2400
	ds_read_b64_tr_b16 v[124:125], v181 offset:0x2c00
	v_mfma_f32_32x32x16_bf16 v[48:63], v[110:113], v[126:129], v[48:63]
	ds_read_b64_tr_b16 v[126:127], v181 offset:0x3400
	ds_read_b64_tr_b16 v[128:129], v181 offset:0x3c00
	s_waitcnt lgkmcnt(0)
	v_mfma_f32_32x32x16_bf16 v[32:47], v[96:99], v[114:117], v[32:47]
	ds_read_b64_tr_b16 v[114:115], v181 offset:0x600
	ds_read_b64_tr_b16 v[116:117], v181 offset:0xe00
	v_mfma_f32_32x32x16_bf16 v[32:47], v[102:105], v[118:121], v[32:47]
	ds_read_b64_tr_b16 v[118:119], v181 offset:0x1600
	ds_read_b64_tr_b16 v[120:121], v181 offset:0x1e00
	v_mfma_f32_32x32x16_bf16 v[32:47], v[106:109], v[122:125], v[32:47]
	ds_read_b64_tr_b16 v[122:123], v181 offset:0x2600
	ds_read_b64_tr_b16 v[124:125], v181 offset:0x2e00
	v_mfma_f32_32x32x16_bf16 v[32:47], v[110:113], v[126:129], v[32:47]
	ds_read_b64_tr_b16 v[126:127], v181 offset:0x3600
	ds_read_b64_tr_b16 v[128:129], v181 offset:0x3e00
	s_waitcnt lgkmcnt(0)
	v_mfma_f32_32x32x16_bf16 v[16:31], v[96:99], v[114:117], v[16:31]
	v_mfma_f32_32x32x16_bf16 v[16:31], v[102:105], v[118:121], v[16:31]
	v_mfma_f32_32x32x16_bf16 v[16:31], v[106:109], v[122:125], v[16:31]
	v_mfma_f32_32x32x16_bf16 v[16:31], v[110:113], v[126:129], v[16:31]
	v_max_f32_e32 v96, v81, v81
	v_max_f32_e32 v97, v80, v80
	v_max_f32_e32 v96, v97, v96
	v_max3_f32 v96, v96, v82, v83
	v_max3_f32 v96, v96, v84, v85
	v_max3_f32 v96, v96, v86, v87
	v_max3_f32 v96, v96, v88, v89
	v_max3_f32 v96, v96, v90, v91
	v_max3_f32 v96, v96, v92, v93
	v_max3_f32 v96, v96, v94, v95
	v_max3_f32 v96, v96, v64, v65
	v_max3_f32 v96, v96, v66, v67
	v_max3_f32 v96, v96, v68, v69
	v_max3_f32 v96, v96, v70, v71
	v_max3_f32 v96, v96, v72, v73
	v_max3_f32 v96, v96, v74, v75
	v_max3_f32 v96, v96, v76, v77
	v_max3_f32 v96, v96, v78, v79
	v_mov_b32_e32 v97, v96
	s_nop 1
	v_permlane32_swap_b32_e32 v96, v97
	v_max_f32_e32 v97, v97, v97
	v_max_f32_e32 v96, v96, v96
	v_max_f32_e32 v96, v96, v97
	v_sub_f32_e32 v97, v96, v207
	v_cmp_ge_f32_e32 vcc, s94, v97
	v_max_f32_e32 v97, v207, v207
	v_max_f32_e32 v96, v97, v96
	v_sub_f32_e32 v97, v207, v96
	v_mul_f32_e32 v97, 0x3dd53b94, v97
	v_exp_f32_e32 v97, v97
	s_cmp_eq_u64 vcc, exec
	s_cselect_b64 s[6:7], -1, 0
	v_cndmask_b32_e64 v97, v97, 1.0, s[6:7]
	v_cmp_gt_f32_e32 vcc, 1.0, v97
	s_barrier
	s_cbranch_vccz .LBB0_776
	s_and_saveexec_b64 s[0:1], s[4:5]
	ds_write_b32 v183, v97 offset:128
	s_or_b64 exec, exec, s[0:1]
	s_waitcnt lgkmcnt(0)
	v_add_u32_e32 v98, v180, v144
	ds_read_b128 v[102:105], v98 offset:224
	ds_read_b128 v[106:109], v98 offset:192
	ds_read_b128 v[110:113], v98 offset:160
	ds_read_b128 v[114:117], v98 offset:128
	s_waitcnt lgkmcnt(3)
	v_pk_mul_f32 v[12:13], v[12:13], v[102:103]
	s_waitcnt lgkmcnt(2)
	v_pk_mul_f32 v[8:9], v[8:9], v[106:107]
	s_waitcnt lgkmcnt(1)
	v_pk_mul_f32 v[4:5], v[4:5], v[110:111]
	v_pk_mul_f32 v[14:15], v[14:15], v[104:105]
	v_pk_mul_f32 v[10:11], v[10:11], v[108:109]
	v_pk_mul_f32 v[6:7], v[6:7], v[112:113]
	s_waitcnt lgkmcnt(0)
	v_pk_mul_f32 v[2:3], v[2:3], v[116:117]
	v_pk_mul_f32 v[0:1], v[0:1], v[114:115]
	v_pk_mul_f32 v[60:61], v[60:61], v[102:103]
	v_pk_mul_f32 v[56:57], v[56:57], v[106:107]
	v_pk_mul_f32 v[52:53], v[52:53], v[110:111]
	v_pk_mul_f32 v[62:63], v[62:63], v[104:105]
	v_pk_mul_f32 v[58:59], v[58:59], v[108:109]
	v_pk_mul_f32 v[54:55], v[54:55], v[112:113]
	v_pk_mul_f32 v[50:51], v[50:51], v[116:117]
	v_pk_mul_f32 v[48:49], v[48:49], v[114:115]
	v_pk_mul_f32 v[44:45], v[44:45], v[102:103]
	v_pk_mul_f32 v[40:41], v[40:41], v[106:107]
	v_pk_mul_f32 v[36:37], v[36:37], v[110:111]
	v_pk_mul_f32 v[46:47], v[46:47], v[104:105]
	v_pk_mul_f32 v[42:43], v[42:43], v[108:109]
	v_pk_mul_f32 v[38:39], v[38:39], v[112:113]
	v_pk_mul_f32 v[34:35], v[34:35], v[116:117]
	v_pk_mul_f32 v[32:33], v[32:33], v[114:115]
	v_pk_mul_f32 v[28:29], v[28:29], v[102:103]
	v_pk_mul_f32 v[24:25], v[24:25], v[106:107]
	v_pk_mul_f32 v[20:21], v[20:21], v[110:111]
	v_pk_mul_f32 v[30:31], v[30:31], v[104:105]
	v_pk_mul_f32 v[26:27], v[26:27], v[108:109]
	v_pk_mul_f32 v[22:23], v[22:23], v[112:113]
	v_pk_mul_f32 v[18:19], v[18:19], v[116:117]
	v_pk_mul_f32 v[16:17], v[16:17], v[114:115]
